# v33 plus stacked wait relocations: GLA1 prep lr read-ahead, EpiUp ssq batch, EpiDownNorm gain+ssq hoist, P0 row loop software prefetch, GLA2 prefetch wait moved to first consumer
# speedup vs baseline: 1.0077x; 1.0069x over previous
; DI unsigned pk2(float lo, float hi) { f32x2 v = {lo, hi}; bf16v2 b = __builtin_convertvector(v, bf16v2); return __builtin_bit_cast(unsigned, b); }
; DI void rms_row2_to_bf16(const float* xrow0, const float* xrow1, const float* g, bf16* orow0, bf16* orow1, int lane) {
;     const f32x4* xr0 = (const f32x4*)xrow0 + lane; const f32x4* xr1 = (const f32x4*)xrow1 + lane; const f32x4* gr = (const f32x4*)g + lane;
;     f32x4 v0[4], v1[4]; float s0 = 0.f, s1 = 0.f;
; #pragma unroll
;     for (int j = 0; j < 4; ++j) { v0[j] = __builtin_nontemporal_load(xr0 + 64 * j); v1[j] = __builtin_nontemporal_load(xr1 + 64 * j); }
; #pragma unroll
;     for (int j = 0; j < 4; ++j) { s0 += (v0[j].x * v0[j].x + v0[j].y * v0[j].y) + (v0[j].z * v0[j].z + v0[j].w * v0[j].w); s1 += (v1[j].x * v1[j].x + v1[j].y * v1[j].y) + (v1[j].z * v1[j].z + v1[j].w * v1[j].w); }
;     const float r0 = rsqrtf(wave_sum(s0) * (1.f / DM) + RMS_EPS), r1 = rsqrtf(wave_sum(s1) * (1.f / DM) + RMS_EPS);
;     u32x2* o0 = (u32x2*)orow0 + lane; u32x2* o1 = (u32x2*)orow1 + lane;
; #pragma unroll
;     for (int j = 0; j < 4; ++j) { const f32x4 gg = gr[64 * j]; u32x2 w;
;         w.x = pk2(v0[j].x * r0 * gg.x, v0[j].y * r0 * gg.y); w.y = pk2(v0[j].z * r0 * gg.z, v0[j].w * r0 * gg.w); o0[64 * j] = w;
;         w.x = pk2(v1[j].x * r1 * gg.x, v1[j].y * r1 * gg.y); w.y = pk2(v1[j].z * r1 * gg.z, v1[j].w * r1 * gg.w); o1[64 * j] = w; }
; __global__ void __launch_bounds__(NTHR, 2) fwd_kernel(Args A) {
;     ...
;         for (int m = gw; m < SBTOK; m += NGW) rms_row2_to_bf16(A.x[0] + (size_t)m * DM, A.x[1] + (size_t)m * DM, A.norm_mix_g, U + (size_t)m * DM, (bf16*)(A.out + (size_t)SBTOK * DM) + (size_t)m * DM, lane);
.LBB0_11:
	s_cmp_eq_u32 s0, s33
	s_mov_b64 s[0:1], -1
	s_cbranch_scc1 .LBB0_16
	s_andn2_b64 vcc, exec, s[36:37]
	s_cbranch_vccnz .LBB0_15
	v_cmp_lt_i32_e32 vcc, v42, v41
	s_mov_b64 s[0:1], s[44:45]
	s_mov_b64 s[50:51], s[18:19]
	v_cndmask_b32_e32 v4, v15, v42, vcc
	v_cmp_lt_i32_e32 vcc, v43, v41
	v_lshlrev_b32_e32 v4, 2, v4
	s_mov_b64 s[52:53], s[16:17]
	v_cndmask_b32_e32 v9, v15, v43, vcc
	v_cmp_lt_i32_e32 vcc, v44, v41
	v_lshlrev_b32_e32 v9, 2, v9
	s_mov_b64 s[54:55], s[22:23]
	v_cndmask_b32_e32 v32, v15, v44, vcc
	v_cmp_lt_i32_e32 vcc, v45, v41
	v_lshlrev_b32_e32 v32, 2, v32
	s_mov_b32 s34, s28
	v_cndmask_b32_e32 v33, v15, v45, vcc
	v_cmp_lt_i32_e32 vcc, v46, v41
	v_lshlrev_b32_e32 v33, 2, v33
	s_nop 0
	v_cndmask_b32_e32 v34, v15, v46, vcc
	v_cmp_lt_i32_e32 vcc, v47, v41
	v_lshlrev_b32_e32 v34, 2, v34
	s_nop 0
	v_cndmask_b32_e32 v48, v15, v47, vcc
	v_lshlrev_b32_e32 v48, 2, v48
	global_load_dwordx4 v[124:127], v[6:7], off
	global_load_dwordx4 v[128:131], v[6:7], off offset:1024
	global_load_dwordx4 v[132:135], v[6:7], off offset:2048
	global_load_dwordx4 v[136:139], v[6:7], off offset:3072
	v_lshl_add_u64 v[172:173], s[52:53], 0, v[2:3]
	v_lshl_add_u64 v[174:175], s[50:51], 0, v[2:3]
	global_load_dwordx4 v[140:143], v[172:173], off nt
	global_load_dwordx4 v[144:147], v[174:175], off nt
	global_load_dwordx4 v[148:151], v[172:173], off offset:1024 nt
	global_load_dwordx4 v[152:155], v[174:175], off offset:1024 nt
	global_load_dwordx4 v[156:159], v[172:173], off offset:3072 nt
	global_load_dwordx4 v[160:163], v[172:173], off offset:2048 nt
	global_load_dwordx4 v[164:167], v[174:175], off offset:3072 nt
	global_load_dwordx4 v[168:171], v[174:175], off offset:2048 nt
	s_add_u32 s52, s52, s42
	s_addc_u32 s53, s53, s43
	s_add_u32 s50, s50, s42
	s_addc_u32 s51, s51, s43
	s_waitcnt vmcnt(0)
.LBB0_14:
	s_waitcnt vmcnt(8)
	v_mov_b64_e32 v[54:55], v[140:141]
	v_mov_b64_e32 v[56:57], v[142:143]
	v_mov_b64_e32 v[58:59], v[144:145]
	v_mov_b64_e32 v[60:61], v[146:147]
	v_mov_b64_e32 v[62:63], v[148:149]
	v_mov_b64_e32 v[64:65], v[150:151]
	v_mov_b64_e32 v[66:67], v[152:153]
	v_mov_b64_e32 v[68:69], v[154:155]
	v_mov_b64_e32 v[70:71], v[156:157]
	v_mov_b64_e32 v[72:73], v[158:159]
	v_mov_b64_e32 v[74:75], v[160:161]
	v_mov_b64_e32 v[76:77], v[162:163]
	v_mov_b64_e32 v[78:79], v[164:165]
	v_mov_b64_e32 v[80:81], v[166:167]
	v_mov_b64_e32 v[82:83], v[168:169]
	v_mov_b64_e32 v[84:85], v[170:171]
	v_lshl_add_u64 v[86:87], s[0:1], 0, v[28:29]
	v_add_co_u32_e32 v86, vcc, s31, v86
	v_lshl_add_u64 v[88:89], s[54:55], 0, v[28:29]
	s_nop 0
	v_addc_co_u32_e32 v87, vcc, 0, v87, vcc
	v_add_co_u32_e32 v88, vcc, s57, v88
	s_nop 1
	v_addc_co_u32_e32 v89, vcc, 0, v89, vcc
	v_lshl_add_u64 v[172:173], s[52:53], 0, v[2:3]
	v_lshl_add_u64 v[174:175], s[50:51], 0, v[2:3]
	s_add_u32 s54, s54, s40
	s_addc_u32 s55, s55, s41
	s_add_u32 s52, s52, s42
	s_addc_u32 s53, s53, s43
	s_add_u32 s50, s50, s42
	s_addc_u32 s51, s51, s43
	s_add_u32 s0, s0, s40
	s_addc_u32 s1, s1, s41
	s_add_i32 s34, s34, s30
	s_cmp_lt_i32 s34, 0x10000
	s_cbranch_scc0 .Lmy_p0_noload
	global_load_dwordx4 v[140:143], v[172:173], off nt
	global_load_dwordx4 v[144:147], v[174:175], off nt
	global_load_dwordx4 v[148:151], v[172:173], off offset:1024 nt
	global_load_dwordx4 v[152:155], v[174:175], off offset:1024 nt
	global_load_dwordx4 v[156:159], v[172:173], off offset:3072 nt
	global_load_dwordx4 v[160:163], v[172:173], off offset:2048 nt
	global_load_dwordx4 v[164:167], v[174:175], off offset:3072 nt
	global_load_dwordx4 v[168:171], v[174:175], off offset:2048 nt
; DI unsigned pk2(float lo, float hi) { f32x2 v = {lo, hi}; bf16v2 b = __builtin_convertvector(v, bf16v2); return __builtin_bit_cast(unsigned, b); }
; DI void rms_row2_to_bf16(const float* xrow0, const float* xrow1, const float* g, bf16* orow0, bf16* orow1, int lane) {
;     const f32x4* xr0 = (const f32x4*)xrow0 + lane; const f32x4* xr1 = (const f32x4*)xrow1 + lane; const f32x4* gr = (const f32x4*)g + lane;
;     f32x4 v0[4], v1[4]; float s0 = 0.f, s1 = 0.f;
; #pragma unroll
;     for (int j = 0; j < 4; ++j) { v0[j] = __builtin_nontemporal_load(xr0 + 64 * j); v1[j] = __builtin_nontemporal_load(xr1 + 64 * j); }
; #pragma unroll
;     for (int j = 0; j < 4; ++j) { s0 += (v0[j].x * v0[j].x + v0[j].y * v0[j].y) + (v0[j].z * v0[j].z + v0[j].w * v0[j].w); s1 += (v1[j].x * v1[j].x + v1[j].y * v1[j].y) + (v1[j].z * v1[j].z + v1[j].w * v1[j].w); }
;     const float r0 = rsqrtf(wave_sum(s0) * (1.f / DM) + RMS_EPS), r1 = rsqrtf(wave_sum(s1) * (1.f / DM) + RMS_EPS);
;     u32x2* o0 = (u32x2*)orow0 + lane; u32x2* o1 = (u32x2*)orow1 + lane;
; #pragma unroll
;     for (int j = 0; j < 4; ++j) { const f32x4 gg = gr[64 * j]; u32x2 w;
;         w.x = pk2(v0[j].x * r0 * gg.x, v0[j].y * r0 * gg.y); w.y = pk2(v0[j].z * r0 * gg.z, v0[j].w * r0 * gg.w); o0[64 * j] = w;
;         w.x = pk2(v1[j].x * r1 * gg.x, v1[j].y * r1 * gg.y); w.y = pk2(v1[j].z * r1 * gg.z, v1[j].w * r1 * gg.w); o1[64 * j] = w; }
; }
.Lmy_p0_noload:
	v_pk_mul_f32 v[90:91], v[56:57], v[56:57]
	v_pk_mul_f32 v[92:93], v[54:55], v[54:55]
	v_pk_mul_f32 v[94:95], v[60:61], v[60:61]
	v_pk_mul_f32 v[96:97], v[58:59], v[58:59]
	v_pk_mul_f32 v[98:99], v[64:65], v[64:65]
	v_pk_mul_f32 v[100:101], v[62:63], v[62:63]
	v_pk_mul_f32 v[102:103], v[68:69], v[68:69]
	v_pk_mul_f32 v[104:105], v[66:67], v[66:67]
	v_pk_mov_b32 v[114:115], v[92:93], v[90:91] op_sel:[1,0]
	v_mov_b32_e32 v93, v91
	v_pk_mov_b32 v[90:91], v[96:97], v[94:95] op_sel:[1,0]
	v_mov_b32_e32 v97, v95
	v_pk_mov_b32 v[94:95], v[100:101], v[98:99] op_sel:[1,0]
	v_mov_b32_e32 v101, v99
	v_pk_mov_b32 v[98:99], v[104:105], v[102:103] op_sel:[1,0]
	v_mov_b32_e32 v105, v103
	v_mul_f32_e32 v113, v71, v71
	v_mul_f32_e32 v106, v75, v75
	v_mul_f32_e32 v108, v77, v77
	v_mul_f32_e32 v110, v83, v83
	v_mul_f32_e32 v112, v85, v85
	v_pk_add_f32 v[92:93], v[114:115], v[92:93]
	v_pk_add_f32 v[90:91], v[90:91], v[96:97]
	v_pk_add_f32 v[94:95], v[94:95], v[100:101]
	v_pk_add_f32 v[96:97], v[98:99], v[104:105]
	v_mul_f32_e32 v49, v70, v70
	v_mul_f32_e32 v116, v72, v72
	v_mul_f32_e32 v117, v73, v73
	v_mul_f32_e32 v118, v78, v78
	v_mul_f32_e32 v119, v79, v79
	v_mul_f32_e32 v120, v80, v80
	v_mul_f32_e32 v121, v81, v81
	v_pk_fma_f32 v[102:103], v[74:75], v[74:75], v[106:107] op_sel_hi:[1,1,0]
	v_pk_fma_f32 v[106:107], v[76:77], v[76:77], v[108:109] op_sel_hi:[1,1,0]
	v_pk_fma_f32 v[108:109], v[82:83], v[82:83], v[110:111] op_sel_hi:[1,1,0]
	v_pk_fma_f32 v[110:111], v[84:85], v[84:85], v[112:113] op_sel_hi:[1,1,0]
	v_pk_add_f32 v[92:93], v[92:93], v[92:93] op_sel:[0,1] op_sel_hi:[1,0]
	v_pk_add_f32 v[94:95], v[94:95], v[94:95] op_sel:[0,1] op_sel_hi:[1,0]
	v_pk_add_f32 v[90:91], v[90:91], v[90:91] op_sel:[0,1] op_sel_hi:[1,0]
	v_pk_add_f32 v[96:97], v[96:97], v[96:97] op_sel:[0,1] op_sel_hi:[1,0]
	v_mov_b32_e32 v103, v116
	v_mov_b32_e32 v107, v117
	v_mov_b32_e32 v109, v120
	v_mov_b32_e32 v111, v121
	v_mov_b32_e32 v93, v49
	v_mov_b32_e32 v95, v113
	v_mov_b32_e32 v91, v118
	v_mov_b32_e32 v97, v119
	v_pk_add_f32 v[98:99], v[102:103], v[106:107]
	v_pk_add_f32 v[100:101], v[108:109], v[110:111]
	v_pk_add_f32 v[92:93], v[92:93], v[94:95]
	v_pk_add_f32 v[90:91], v[90:91], v[96:97]
	v_pk_add_f32 v[92:93], v[92:93], v[98:99]
	v_pk_add_f32 v[90:91], v[90:91], v[100:101]
	v_mov_b32_e32 v95, v92
	v_mov_b32_e32 v94, v90
	v_mov_b32_e32 v92, v91
	v_pk_add_f32 v[90:91], v[94:95], v[92:93]
	ds_bpermute_b32 v93, v4, v91
	ds_bpermute_b32 v92, v4, v90
	s_waitcnt lgkmcnt(0)
	v_pk_add_f32 v[90:91], v[90:91], v[92:93]
	ds_bpermute_b32 v93, v9, v91
	ds_bpermute_b32 v92, v9, v90
	s_waitcnt lgkmcnt(0)
	v_pk_add_f32 v[90:91], v[90:91], v[92:93]
	ds_bpermute_b32 v93, v32, v91
	ds_bpermute_b32 v92, v32, v90
	s_waitcnt lgkmcnt(0)
	v_pk_add_f32 v[90:91], v[90:91], v[92:93]
	ds_bpermute_b32 v93, v33, v91
	ds_bpermute_b32 v92, v33, v90
	s_waitcnt lgkmcnt(0)
	v_pk_add_f32 v[90:91], v[90:91], v[92:93]
	ds_bpermute_b32 v93, v34, v91
	ds_bpermute_b32 v92, v34, v90
	s_waitcnt lgkmcnt(0)
	v_pk_add_f32 v[90:91], v[90:91], v[92:93]
	ds_bpermute_b32 v93, v48, v91
	ds_bpermute_b32 v92, v48, v90
	s_waitcnt lgkmcnt(0)
	v_pk_add_f32 v[90:91], v[90:91], v[92:93]
	s_nop 0
	v_pk_fma_f32 v[90:91], v[90:91], s[46:47], v[30:31] op_sel_hi:[1,0,0]
	s_nop 0
	v_mul_f32_e32 v49, 0x4b800000, v91
	v_cmp_gt_f32_e64 s[4:5], s29, v91
	v_mul_f32_e32 v92, 0x4b800000, v90
	v_cmp_gt_f32_e32 vcc, s29, v90
	v_cndmask_b32_e64 v49, v91, v49, s[4:5]
	v_rsq_f32_e32 v49, v49
	v_cndmask_b32_e32 v90, v90, v92, vcc
	v_rsq_f32_e32 v91, v90
	v_mul_f32_e32 v90, 0x45800000, v49
	v_cndmask_b32_e64 v90, v49, v90, s[4:5]
	v_mul_f32_e32 v92, 0x45800000, v91
	v_cndmask_b32_e32 v92, v91, v92, vcc
	v_pk_mul_f32 v[54:55], v[54:55], v[90:91] op_sel_hi:[1,0]
	v_pk_mul_f32 v[56:57], v[56:57], v[90:91] op_sel_hi:[1,0]
	v_pk_mul_f32 v[58:59], v[58:59], v[92:93] op_sel_hi:[1,0]
	v_pk_mul_f32 v[60:61], v[60:61], v[92:93] op_sel_hi:[1,0]
	v_pk_mul_f32 v[54:55], v[124:125], v[54:55]
	v_pk_mul_f32 v[56:57], v[126:127], v[56:57]
	v_pk_mul_f32 v[50:51], v[124:125], v[58:59]
	v_pk_mul_f32 v[52:53], v[126:127], v[60:61]
	v_cvt_pk_bf16_f32 v54, v54, v55
	v_cvt_pk_bf16_f32 v55, v56, v57
	v_cvt_pk_bf16_f32 v50, v50, v51
	v_cvt_pk_bf16_f32 v51, v52, v53
	global_store_dwordx2 v[86:87], v[54:55], off
	global_store_dwordx2 v[88:89], v[50:51], off
	v_pk_mul_f32 v[54:55], v[62:63], v[90:91] op_sel_hi:[1,0]
	v_pk_mul_f32 v[56:57], v[64:65], v[90:91] op_sel_hi:[1,0]
	v_pk_mul_f32 v[58:59], v[66:67], v[92:93] op_sel_hi:[1,0]
	v_pk_mul_f32 v[60:61], v[68:69], v[92:93] op_sel_hi:[1,0]
	v_pk_mul_f32 v[54:55], v[54:55], v[128:129]
	v_pk_mul_f32 v[56:57], v[56:57], v[130:131]
	v_pk_mul_f32 v[50:51], v[128:129], v[58:59]
	v_pk_mul_f32 v[52:53], v[130:131], v[60:61]
	v_cvt_pk_bf16_f32 v54, v54, v55
	v_cvt_pk_bf16_f32 v55, v56, v57
	v_cvt_pk_bf16_f32 v50, v50, v51
	v_cvt_pk_bf16_f32 v51, v52, v53
	global_store_dwordx2 v[86:87], v[54:55], off offset:512
	global_store_dwordx2 v[88:89], v[50:51], off offset:512
	v_pk_mul_f32 v[54:55], v[74:75], v[90:91] op_sel_hi:[1,0]
	v_pk_mul_f32 v[56:57], v[76:77], v[90:91] op_sel_hi:[1,0]
	v_pk_mul_f32 v[58:59], v[82:83], v[92:93] op_sel_hi:[1,0]
	v_pk_mul_f32 v[60:61], v[84:85], v[92:93] op_sel_hi:[1,0]
	v_pk_mul_f32 v[54:55], v[54:55], v[132:133]
	v_pk_mul_f32 v[56:57], v[56:57], v[134:135]
	v_pk_mul_f32 v[50:51], v[132:133], v[58:59]
	v_pk_mul_f32 v[52:53], v[134:135], v[60:61]
	v_cvt_pk_bf16_f32 v54, v54, v55
	v_cvt_pk_bf16_f32 v55, v56, v57
	v_cvt_pk_bf16_f32 v50, v50, v51
	v_cvt_pk_bf16_f32 v51, v52, v53
	global_store_dwordx2 v[86:87], v[54:55], off offset:1024
	global_store_dwordx2 v[88:89], v[50:51], off offset:1024
	v_pk_mul_f32 v[54:55], v[70:71], v[90:91] op_sel_hi:[1,0]
	v_pk_mul_f32 v[56:57], v[72:73], v[90:91] op_sel_hi:[1,0]
	v_pk_mul_f32 v[58:59], v[78:79], v[92:93] op_sel_hi:[1,0]
	v_pk_mul_f32 v[60:61], v[80:81], v[92:93] op_sel_hi:[1,0]
	v_pk_mul_f32 v[54:55], v[54:55], v[136:137]
	v_pk_mul_f32 v[56:57], v[56:57], v[138:139]
	v_pk_mul_f32 v[50:51], v[58:59], v[136:137]
	v_pk_mul_f32 v[52:53], v[60:61], v[138:139]
	v_cvt_pk_bf16_f32 v54, v54, v55
	v_cvt_pk_bf16_f32 v55, v56, v57
	v_cvt_pk_bf16_f32 v50, v50, v51
	v_cvt_pk_bf16_f32 v51, v52, v53
	global_store_dwordx2 v[86:87], v[54:55], off offset:1536
	global_store_dwordx2 v[88:89], v[50:51], off offset:1536
	s_cbranch_scc1 .LBB0_14

; __device__ __forceinline__ float bf2f(unsigned short b) { return __uint_as_float((unsigned)b << 16); }
; #define LAS __attribute__((address_space(3)))
; DI float bf2f(unsigned short b) { return __uint_as_float((unsigned)b << 16); }
; DI unsigned short f2bf(float x) { return (unsigned short)(pk2(x, 0.f) & 0xffffu); }
; DI float fexp_(float x) { return __builtin_amdgcn_exp2f(1.4426950408889634f * x); }
; DI float logsigmoid_(float x) { return fminf(x, 0.f) - 0.6931471805599453f * __builtin_amdgcn_logf(1.0f + fexp_(-fabsf(x))); }
; DI void gla_pass1(LAS unsigned char* lds, const Args& A, const bf16* proj, bf16* scratch, bf16* QS, bf16* HT, float* DD, int T, int b, int h, int k, int tid_in) {
;     ...
;             for (int i = 0; i < 16; ++i) {
;                 const LAS u32x4* lr4 = (const LAS u32x4*)(L + GL_LR + (c * 16 + i) * 32);
;                 const u32x4 la_ = lr4[0], lb_ = lr4[1];
;                 const unsigned lw[8] = {la_.x, la_.y, la_.z, la_.w, lb_.x, lb_.y, lb_.z, lb_.w};
;                 float pre = gkb;
; #pragma unroll
;                 for (int j = 0; j < 8; ++j) pre = __builtin_amdgcn_fdot2_f32_bf16(__builtin_bit_cast(bf16v2, lw[j]), __builtin_bit_cast(bf16v2, gkp[j]), pre, false);
;                 cum += logsigmoid_(pre) * (1.0f / 16.0f);
;                 const float e = fexp_(cum); qdv[i] = bf2f(qraw[i]) * e;
;                 kinv[i] = bf2f(kraw[i]) * __builtin_amdgcn_rcpf(e);
;                 *(LAS unsigned short*)(L + GL_QD + (c * 16 + i) * GL_P + d * 2) = f2bf(qdv[i]);
;                 *(LAS unsigned short*)(L + GL_KI + (c * 16 + i) * GL_P + d * 2) = f2bf(kinv[i]);
;             }
.LBB0_417:
	s_waitcnt vmcnt(4)
	ds_write_b64 v155, v[80:81] offset:47104
	s_waitcnt lgkmcnt(0)
	v_add_u32_e32 v52, v90, v141
	ds_read_b128 v[178:181], v52 offset:47104
	ds_read_b128 v[182:185], v52 offset:47120
	ds_read_b128 v[186:189], v157 offset:47104
	ds_read_b128 v[252:255], v157 offset:47120
	v_mov_b32_e32 v56, v98
	s_mov_b32 s1, 0x3d800000
	v_mov_b32_e32 v58, v98
	s_waitcnt lgkmcnt(2)
	v_dot2c_f32_bf16_e32 v56, v178, v99
	v_dot2c_f32_bf16_e32 v56, v179, v100
	v_dot2c_f32_bf16_e32 v56, v180, v101
	v_dot2c_f32_bf16_e32 v56, v181, v102
	v_dot2c_f32_bf16_e32 v56, v182, v103
	v_dot2c_f32_bf16_e32 v56, v183, v104
	v_dot2c_f32_bf16_e32 v56, v184, v105
	v_dot2c_f32_bf16_e32 v56, v185, v106
	v_mov_b32_e32 v82, v98
	v_mov_b32_e32 v86, v98
	s_cmpk_eq_i32 s66, 0x3c0
	v_mul_f32_e64 v49, |v56|, s84
	v_exp_f32_e32 v49, v49
	v_max_f32_e32 v48, v56, v56
	v_min_f32_e32 v48, 0, v48
	v_add_f32_e32 v49, 1.0, v49
	v_log_f32_e32 v49, v49
	s_nop 0
	v_fmac_f32_e32 v48, 0xbf317218, v49
	v_fma_f32 v238, v48, s1, 0
	v_mul_f32_e32 v48, 0x3fb8aa3b, v238
	v_exp_f32_e32 v48, v48
	v_lshlrev_b32_e32 v49, 16, v107
	v_mul_f32_e32 v233, v48, v49
	v_cvt_pk_bf16_f32 v49, v233, s0
	ds_write_b16 v156, v49
	ds_read_b128 v[178:181], v159 offset:47104
	ds_read_b128 v[182:185], v159 offset:47120
	v_mov_b32_e32 v49, v98
	v_rcp_f32_e32 v48, v48
	s_waitcnt lgkmcnt(2)
	v_dot2c_f32_bf16_e32 v49, v186, v99
	v_dot2c_f32_bf16_e32 v49, v187, v100
	v_dot2c_f32_bf16_e32 v49, v188, v101
	v_dot2c_f32_bf16_e32 v49, v189, v102
	v_dot2c_f32_bf16_e32 v49, v252, v103
	v_dot2c_f32_bf16_e32 v49, v253, v104
	v_dot2c_f32_bf16_e32 v49, v254, v105
	v_dot2c_f32_bf16_e32 v49, v255, v106
	s_nop 2
	v_max_f32_e32 v50, v49, v49
	v_mul_f32_e64 v49, |v49|, s84
	v_exp_f32_e32 v49, v49
	v_min_f32_e32 v50, 0, v50
	v_add_f32_e32 v49, 1.0, v49
	v_log_f32_e32 v49, v49
	s_nop 0
	v_fmac_f32_e32 v50, 0xbf317218, v49
	v_fmac_f32_e32 v238, 0x3d800000, v50
	v_mul_f32_e32 v49, 0x3fb8aa3b, v238
	v_exp_f32_e32 v49, v49
	v_lshlrev_b32_e32 v50, 16, v109
	v_mul_f32_e32 v231, v49, v50
	v_cvt_pk_bf16_f32 v50, v231, s0
	ds_write_b16 v158, v50
	ds_read_b128 v[186:189], v160 offset:47104
	ds_read_b128 v[252:255], v160 offset:47120
	v_rcp_f32_e32 v49, v49
	s_waitcnt lgkmcnt(2)
	v_dot2c_f32_bf16_e32 v58, v178, v99
	v_dot2c_f32_bf16_e32 v58, v179, v100
	v_dot2c_f32_bf16_e32 v58, v180, v101
	v_dot2c_f32_bf16_e32 v58, v181, v102
	v_dot2c_f32_bf16_e32 v58, v182, v103
	v_dot2c_f32_bf16_e32 v58, v183, v104
	v_dot2c_f32_bf16_e32 v58, v184, v105
	v_dot2c_f32_bf16_e32 v58, v185, v106
	s_nop 2
	v_mul_f32_e64 v51, |v58|, s84
	v_exp_f32_e32 v51, v51
	v_max_f32_e32 v50, v58, v58
	v_min_f32_e32 v50, 0, v50
	v_add_f32_e32 v51, 1.0, v51
	v_log_f32_e32 v51, v51
	s_nop 0
	v_fmac_f32_e32 v50, 0xbf317218, v51
	v_fmac_f32_e32 v238, 0x3d800000, v50
	v_mul_f32_e32 v50, 0x3fb8aa3b, v238
	v_exp_f32_e32 v50, v50
	v_lshlrev_b32_e32 v51, 16, v113
	v_mul_f32_e32 v87, v50, v51
	v_cvt_pk_bf16_f32 v51, v87, s0
	ds_write_b16 v158, v51 offset:144
	ds_read_b128 v[178:181], v161 offset:47104
	ds_read_b128 v[182:185], v161 offset:47120
	v_mov_b32_e32 v51, v98
	v_rcp_f32_e32 v50, v50
	s_waitcnt lgkmcnt(2)
	v_dot2c_f32_bf16_e32 v51, v186, v99
	v_dot2c_f32_bf16_e32 v51, v187, v100
	v_dot2c_f32_bf16_e32 v51, v188, v101
	v_dot2c_f32_bf16_e32 v51, v189, v102
	v_dot2c_f32_bf16_e32 v51, v252, v103
	v_dot2c_f32_bf16_e32 v51, v253, v104
	v_dot2c_f32_bf16_e32 v51, v254, v105
	v_dot2c_f32_bf16_e32 v51, v255, v106
	s_nop 2
	v_max_f32_e32 v52, v51, v51
	v_mul_f32_e64 v51, |v51|, s84
	v_exp_f32_e32 v51, v51
	v_min_f32_e32 v52, 0, v52
	v_add_f32_e32 v51, 1.0, v51
	v_log_f32_e32 v51, v51
	s_nop 0
	v_fmac_f32_e32 v52, 0xbf317218, v51
	v_fmac_f32_e32 v238, 0x3d800000, v52
	v_mul_f32_e32 v51, 0x3fb8aa3b, v238
	v_exp_f32_e32 v51, v51
	v_lshlrev_b32_e32 v52, 16, v116
	v_mul_f32_e32 v88, v51, v52
	v_cvt_pk_bf16_f32 v52, v88, s0
	ds_write_b16 v158, v52 offset:288
	ds_read_b128 v[186:189], v162 offset:47104
	ds_read_b128 v[252:255], v162 offset:47120
	v_rcp_f32_e32 v51, v51
	s_waitcnt lgkmcnt(2)
	v_dot2c_f32_bf16_e32 v82, v178, v99
	v_dot2c_f32_bf16_e32 v82, v179, v100
	v_dot2c_f32_bf16_e32 v82, v180, v101
	v_dot2c_f32_bf16_e32 v82, v181, v102
	v_dot2c_f32_bf16_e32 v82, v182, v103
	v_dot2c_f32_bf16_e32 v82, v183, v104
	v_dot2c_f32_bf16_e32 v82, v184, v105
	v_dot2c_f32_bf16_e32 v82, v185, v106
	v_mov_b32_e32 v58, v98
	s_nop 1
	v_mul_f32_e64 v53, |v82|, s84
	v_exp_f32_e32 v53, v53
	v_max_f32_e32 v52, v82, v82
	v_min_f32_e32 v52, 0, v52
	v_add_f32_e32 v53, 1.0, v53
	v_log_f32_e32 v53, v53
	s_nop 0
	v_fmac_f32_e32 v52, 0xbf317218, v53
	v_fmac_f32_e32 v238, 0x3d800000, v52
	v_mul_f32_e32 v52, 0x3fb8aa3b, v238
	v_exp_f32_e32 v52, v52
	v_lshlrev_b32_e32 v53, 16, v119
	v_mul_f32_e32 v89, v52, v53
	v_cvt_pk_bf16_f32 v53, v89, s0
	ds_write_b16 v158, v53 offset:432
	ds_read_b128 v[178:181], v163 offset:47104
	ds_read_b128 v[182:185], v163 offset:47120
	v_mov_b32_e32 v53, v98
	v_rcp_f32_e32 v52, v52
	s_waitcnt lgkmcnt(2)
	v_dot2c_f32_bf16_e32 v53, v186, v99
	v_dot2c_f32_bf16_e32 v53, v187, v100
	v_dot2c_f32_bf16_e32 v53, v188, v101
	v_dot2c_f32_bf16_e32 v53, v189, v102
	v_dot2c_f32_bf16_e32 v53, v252, v103
	v_dot2c_f32_bf16_e32 v53, v253, v104
	v_dot2c_f32_bf16_e32 v53, v254, v105
	v_dot2c_f32_bf16_e32 v53, v255, v106
	s_nop 2
	v_max_f32_e32 v54, v53, v53
	v_mul_f32_e64 v53, |v53|, s84
	v_exp_f32_e32 v53, v53
	v_min_f32_e32 v54, 0, v54
	v_add_f32_e32 v53, 1.0, v53
	v_log_f32_e32 v53, v53
	s_nop 0
	v_fmac_f32_e32 v54, 0xbf317218, v53
	v_fmac_f32_e32 v238, 0x3d800000, v54
	v_mul_f32_e32 v53, 0x3fb8aa3b, v238
	v_exp_f32_e32 v53, v53
	v_lshlrev_b32_e32 v54, 16, v121
	v_mul_f32_e32 v225, v53, v54
	v_cvt_pk_bf16_f32 v54, v225, s0
	ds_write_b16 v158, v54 offset:576
	ds_read_b128 v[186:189], v164 offset:47104
	ds_read_b128 v[252:255], v164 offset:47120
	v_rcp_f32_e32 v53, v53
	s_waitcnt lgkmcnt(2)
; __device__ __forceinline__ float bf2f(unsigned short b) { return __uint_as_float((unsigned)b << 16); }
; #define LAS __attribute__((address_space(3)))
; DI float bf2f(unsigned short b) { return __uint_as_float((unsigned)b << 16); }
; DI unsigned short f2bf(float x) { return (unsigned short)(pk2(x, 0.f) & 0xffffu); }
; DI float fexp_(float x) { return __builtin_amdgcn_exp2f(1.4426950408889634f * x); }
; DI float logsigmoid_(float x) { return fminf(x, 0.f) - 0.6931471805599453f * __builtin_amdgcn_logf(1.0f + fexp_(-fabsf(x))); }
; DI void gla_pass1(LAS unsigned char* lds, const Args& A, const bf16* proj, bf16* scratch, bf16* QS, bf16* HT, float* DD, int T, int b, int h, int k, int tid_in) {
;     ...
;             for (int i = 0; i < 16; ++i) {
;                 const LAS u32x4* lr4 = (const LAS u32x4*)(L + GL_LR + (c * 16 + i) * 32);
;                 const u32x4 la_ = lr4[0], lb_ = lr4[1];
;                 const unsigned lw[8] = {la_.x, la_.y, la_.z, la_.w, lb_.x, lb_.y, lb_.z, lb_.w};
;                 float pre = gkb;
; #pragma unroll
;                 for (int j = 0; j < 8; ++j) pre = __builtin_amdgcn_fdot2_f32_bf16(__builtin_bit_cast(bf16v2, lw[j]), __builtin_bit_cast(bf16v2, gkp[j]), pre, false);
;                 cum += logsigmoid_(pre) * (1.0f / 16.0f);
;                 const float e = fexp_(cum); qdv[i] = bf2f(qraw[i]) * e;
;                 kinv[i] = bf2f(kraw[i]) * __builtin_amdgcn_rcpf(e);
;                 *(LAS unsigned short*)(L + GL_QD + (c * 16 + i) * GL_P + d * 2) = f2bf(qdv[i]);
;                 *(LAS unsigned short*)(L + GL_KI + (c * 16 + i) * GL_P + d * 2) = f2bf(kinv[i]);
;             }
	v_dot2c_f32_bf16_e32 v58, v178, v99
	v_dot2c_f32_bf16_e32 v58, v179, v100
	v_dot2c_f32_bf16_e32 v58, v180, v101
	v_dot2c_f32_bf16_e32 v58, v181, v102
	v_dot2c_f32_bf16_e32 v58, v182, v103
	v_dot2c_f32_bf16_e32 v58, v183, v104
	v_dot2c_f32_bf16_e32 v58, v184, v105
	v_dot2c_f32_bf16_e32 v58, v185, v106
	s_nop 2
	v_mul_f32_e64 v55, |v58|, s84
	v_exp_f32_e32 v55, v55
	v_max_f32_e32 v54, v58, v58
	v_min_f32_e32 v54, 0, v54
	v_add_f32_e32 v55, 1.0, v55
	v_log_f32_e32 v55, v55
	s_nop 0
	v_fmac_f32_e32 v54, 0xbf317218, v55
	v_fmac_f32_e32 v238, 0x3d800000, v54
	v_mul_f32_e32 v54, 0x3fb8aa3b, v238
	v_exp_f32_e32 v54, v54
	v_lshlrev_b32_e32 v55, 16, v127
	v_mul_f32_e32 v226, v54, v55
	v_cvt_pk_bf16_f32 v55, v226, s0
	ds_write_b16 v158, v55 offset:720
	ds_read_b128 v[178:181], v165 offset:47104
	ds_read_b128 v[182:185], v165 offset:47120
	v_mov_b32_e32 v55, v98
	v_rcp_f32_e32 v54, v54
	s_waitcnt lgkmcnt(2)
	v_dot2c_f32_bf16_e32 v55, v186, v99
	v_dot2c_f32_bf16_e32 v55, v187, v100
	v_dot2c_f32_bf16_e32 v55, v188, v101
	v_dot2c_f32_bf16_e32 v55, v189, v102
	v_dot2c_f32_bf16_e32 v55, v252, v103
	v_dot2c_f32_bf16_e32 v55, v253, v104
	v_dot2c_f32_bf16_e32 v55, v254, v105
	v_dot2c_f32_bf16_e32 v55, v255, v106
	s_nop 2
	v_max_f32_e32 v56, v55, v55
	v_mul_f32_e64 v55, |v55|, s84
	v_exp_f32_e32 v55, v55
	v_min_f32_e32 v56, 0, v56
	v_add_f32_e32 v55, 1.0, v55
	v_log_f32_e32 v55, v55
	s_nop 0
	v_fmac_f32_e32 v56, 0xbf317218, v55
	v_fmac_f32_e32 v238, 0x3d800000, v56
	v_mul_f32_e32 v55, 0x3fb8aa3b, v238
	v_exp_f32_e32 v55, v55
	v_lshlrev_b32_e32 v56, 16, v137
	v_mul_f32_e32 v227, v55, v56
	v_cvt_pk_bf16_f32 v56, v227, s0
	ds_write_b16 v158, v56 offset:864
	ds_read_b128 v[186:189], v166 offset:47104
	ds_read_b128 v[252:255], v166 offset:47120
	v_rcp_f32_e32 v55, v55
	s_waitcnt lgkmcnt(2)
	v_dot2c_f32_bf16_e32 v86, v178, v99
	v_dot2c_f32_bf16_e32 v86, v179, v100
	v_dot2c_f32_bf16_e32 v86, v180, v101
	v_dot2c_f32_bf16_e32 v86, v181, v102
	v_dot2c_f32_bf16_e32 v86, v182, v103
	v_dot2c_f32_bf16_e32 v86, v183, v104
	v_dot2c_f32_bf16_e32 v86, v184, v105
	v_dot2c_f32_bf16_e32 v86, v185, v106
	s_nop 2
	v_mul_f32_e64 v57, |v86|, s84
	v_exp_f32_e32 v57, v57
	v_max_f32_e32 v56, v86, v86
	v_min_f32_e32 v56, 0, v56
	v_mov_b32_e32 v86, v98
	v_add_f32_e32 v57, 1.0, v57
	v_log_f32_e32 v57, v57
	s_nop 0
	v_fmac_f32_e32 v56, 0xbf317218, v57
	v_fmac_f32_e32 v238, 0x3d800000, v56
	v_mul_f32_e32 v56, 0x3fb8aa3b, v238
	v_exp_f32_e32 v56, v56
	v_lshlrev_b32_e32 v57, 16, v142
	v_mul_f32_e32 v228, v56, v57
	v_cvt_pk_bf16_f32 v57, v228, s0
	ds_write_b16 v158, v57 offset:1008
	ds_read_b128 v[178:181], v167 offset:47104
	ds_read_b128 v[182:185], v167 offset:47120
	v_mov_b32_e32 v57, v98
	v_rcp_f32_e32 v56, v56
	s_waitcnt lgkmcnt(2)
	v_dot2c_f32_bf16_e32 v57, v186, v99
	v_dot2c_f32_bf16_e32 v57, v187, v100
	v_dot2c_f32_bf16_e32 v57, v188, v101
	v_dot2c_f32_bf16_e32 v57, v189, v102
	v_dot2c_f32_bf16_e32 v57, v252, v103
	v_dot2c_f32_bf16_e32 v57, v253, v104
	v_dot2c_f32_bf16_e32 v57, v254, v105
	v_dot2c_f32_bf16_e32 v57, v255, v106
	s_nop 2
	v_max_f32_e32 v58, v57, v57
	v_mul_f32_e64 v57, |v57|, s84
	v_exp_f32_e32 v57, v57
	v_min_f32_e32 v58, 0, v58
	v_add_f32_e32 v57, 1.0, v57
	v_log_f32_e32 v57, v57
	s_nop 0
	v_fmac_f32_e32 v58, 0xbf317218, v57
	v_fmac_f32_e32 v238, 0x3d800000, v58
	v_mul_f32_e32 v57, 0x3fb8aa3b, v238
	v_exp_f32_e32 v57, v57
	v_lshlrev_b32_e32 v58, 16, v143
	v_mul_f32_e32 v229, v57, v58
	v_cvt_pk_bf16_f32 v58, v229, s0
	ds_write_b16 v158, v58 offset:1152
	ds_read_b128 v[186:189], v168 offset:47104
	ds_read_b128 v[252:255], v168 offset:47120
	v_mov_b32_e32 v58, v98
	v_rcp_f32_e32 v57, v57
	s_waitcnt lgkmcnt(2)
	v_dot2c_f32_bf16_e32 v58, v178, v99
	v_dot2c_f32_bf16_e32 v58, v179, v100
	v_dot2c_f32_bf16_e32 v58, v180, v101
	v_dot2c_f32_bf16_e32 v58, v181, v102
	v_dot2c_f32_bf16_e32 v58, v182, v103
	v_dot2c_f32_bf16_e32 v58, v183, v104
	v_dot2c_f32_bf16_e32 v58, v184, v105
	v_dot2c_f32_bf16_e32 v58, v185, v106
	s_nop 2
	v_max_f32_e32 v59, v58, v58
	v_mul_f32_e64 v58, |v58|, s84
	v_exp_f32_e32 v58, v58
	v_min_f32_e32 v59, 0, v59
	v_add_f32_e32 v58, 1.0, v58
	v_log_f32_e32 v58, v58
	s_nop 0
	v_fmac_f32_e32 v59, 0xbf317218, v58
	v_fmac_f32_e32 v238, 0x3d800000, v59
	v_mul_f32_e32 v58, 0x3fb8aa3b, v238
	v_exp_f32_e32 v58, v58
	v_lshlrev_b32_e32 v59, 16, v197
	v_mul_f32_e32 v230, v58, v59
	v_cvt_pk_bf16_f32 v59, v230, s0
	ds_write_b16 v158, v59 offset:1296
	ds_read_b128 v[178:181], v169 offset:47104
	ds_read_b128 v[182:185], v169 offset:47120
	v_mov_b32_e32 v59, v98
	v_rcp_f32_e32 v58, v58
	s_waitcnt lgkmcnt(2)
	v_dot2c_f32_bf16_e32 v59, v186, v99
	v_dot2c_f32_bf16_e32 v59, v187, v100
	v_dot2c_f32_bf16_e32 v59, v188, v101
	v_dot2c_f32_bf16_e32 v59, v189, v102
	v_dot2c_f32_bf16_e32 v59, v252, v103
	v_dot2c_f32_bf16_e32 v59, v253, v104
	v_dot2c_f32_bf16_e32 v59, v254, v105
	v_dot2c_f32_bf16_e32 v59, v255, v106
	s_nop 2
	v_max_f32_e32 v82, v59, v59
	v_mul_f32_e64 v59, |v59|, s84
	v_exp_f32_e32 v59, v59
	v_min_f32_e32 v82, 0, v82
	v_add_f32_e32 v59, 1.0, v59
	v_log_f32_e32 v59, v59
	s_nop 0
	v_fmac_f32_e32 v82, 0xbf317218, v59
	v_fmac_f32_e32 v238, 0x3d800000, v82
	v_mul_f32_e32 v59, 0x3fb8aa3b, v238
	v_exp_f32_e32 v59, v59
	v_lshlrev_b32_e32 v82, 16, v205
	v_mul_f32_e32 v232, v59, v82
	v_cvt_pk_bf16_f32 v82, v232, s0
	ds_write_b16 v158, v82 offset:1440
	ds_read_b128 v[186:189], v170 offset:47104
	ds_read_b128 v[252:255], v170 offset:47120
	v_rcp_f32_e32 v59, v59
	s_waitcnt lgkmcnt(2)
; __device__ __forceinline__ float bf2f(unsigned short b) { return __uint_as_float((unsigned)b << 16); }
; #define LAS __attribute__((address_space(3)))
; DI float bf2f(unsigned short b) { return __uint_as_float((unsigned)b << 16); }
; DI unsigned pk2(float lo, float hi) { f32x2 v = {lo, hi}; bf16v2 b = __builtin_convertvector(v, bf16v2); return __builtin_bit_cast(unsigned, b); }
; DI unsigned short f2bf(float x) { return (unsigned short)(pk2(x, 0.f) & 0xffffu); }
; DI float fexp_(float x) { return __builtin_amdgcn_exp2f(1.4426950408889634f * x); }
; DI void gla_pass1(LAS unsigned char* lds, const Args& A, const bf16* proj, bf16* scratch, bf16* QS, bf16* HT, float* DD, int T, int b, int h, int k, int tid_in) {
;     ...
;             for (int i = 0; i < 16; ++i) {
;                 const LAS u32x4* lr4 = (const LAS u32x4*)(L + GL_LR + (c * 16 + i) * 32);
;                 const u32x4 la_ = lr4[0], lb_ = lr4[1];
;                 const unsigned lw[8] = {la_.x, la_.y, la_.z, la_.w, lb_.x, lb_.y, lb_.z, lb_.w};
;                 float pre = gkb;
; #pragma unroll
;                 for (int j = 0; j < 8; ++j) pre = __builtin_amdgcn_fdot2_f32_bf16(__builtin_bit_cast(bf16v2, lw[j]), __builtin_bit_cast(bf16v2, gkp[j]), pre, false);
;                 cum += logsigmoid_(pre) * (1.0f / 16.0f);
;                 const float e = fexp_(cum); qdv[i] = bf2f(qraw[i]) * e;
;                 kinv[i] = bf2f(kraw[i]) * __builtin_amdgcn_rcpf(e);
;                 *(LAS unsigned short*)(L + GL_QD + (c * 16 + i) * GL_P + d * 2) = f2bf(qdv[i]);
;                 *(LAS unsigned short*)(L + GL_KI + (c * 16 + i) * GL_P + d * 2) = f2bf(kinv[i]);
;             }
;             const float eL = fexp_(cum);
;             ((LAS float*)(L + GL_DEC))[c * 64 + d] = eL;
;             ((LAS float*)(L + GL_CL))[c * 64 + d] = cum;
;             u32x4 w0, w1;
;             w0.x = pk2(kinv[0] * eL, kinv[1] * eL); w0.y = pk2(kinv[2] * eL, kinv[3] * eL); w0.z = pk2(kinv[4] * eL, kinv[5] * eL); w0.w = pk2(kinv[6] * eL, kinv[7] * eL);
;             w1.x = pk2(kinv[8] * eL, kinv[9] * eL); w1.y = pk2(kinv[10] * eL, kinv[11] * eL); w1.z = pk2(kinv[12] * eL, kinv[13] * eL); w1.w = pk2(kinv[14] * eL, kinv[15] * eL);
;             *(LAS u32x4*)(L + GL_KDT + d * GL_P + c * 32) = w0; *(LAS u32x4*)(L + GL_KDT + d * GL_P + c * 32 + 16) = w1;
	v_dot2c_f32_bf16_e32 v86, v178, v99
	v_dot2c_f32_bf16_e32 v86, v179, v100
	v_dot2c_f32_bf16_e32 v86, v180, v101
	v_dot2c_f32_bf16_e32 v86, v181, v102
	v_dot2c_f32_bf16_e32 v86, v182, v103
	v_dot2c_f32_bf16_e32 v86, v183, v104
	v_dot2c_f32_bf16_e32 v86, v184, v105
	v_dot2c_f32_bf16_e32 v86, v185, v106
	s_nop 2
	v_mul_f32_e64 v83, |v86|, s84
	v_exp_f32_e32 v83, v83
	v_max_f32_e32 v82, v86, v86
	v_min_f32_e32 v82, 0, v82
	v_add_f32_e32 v83, 1.0, v83
	v_log_f32_e32 v83, v83
	s_nop 0
	v_fmac_f32_e32 v82, 0xbf317218, v83
	v_fmac_f32_e32 v238, 0x3d800000, v82
	v_mul_f32_e32 v82, 0x3fb8aa3b, v238
	v_exp_f32_e32 v82, v82
	v_lshlrev_b32_e32 v83, 16, v206
	v_mul_f32_e32 v234, v82, v83
	v_cvt_pk_bf16_f32 v83, v234, s0
	ds_write_b16 v158, v83 offset:1584
	ds_read_b128 v[178:181], v171 offset:47104
	ds_read_b128 v[182:185], v171 offset:47120
	v_mov_b32_e32 v83, v98
	v_rcp_f32_e32 v82, v82
	s_waitcnt lgkmcnt(2)
	v_dot2c_f32_bf16_e32 v83, v186, v99
	v_dot2c_f32_bf16_e32 v83, v187, v100
	v_dot2c_f32_bf16_e32 v83, v188, v101
	v_dot2c_f32_bf16_e32 v83, v189, v102
	v_dot2c_f32_bf16_e32 v83, v252, v103
	v_dot2c_f32_bf16_e32 v83, v253, v104
	v_dot2c_f32_bf16_e32 v83, v254, v105
	v_dot2c_f32_bf16_e32 v83, v255, v106
	s_nop 2
	v_max_f32_e32 v84, v83, v83
	v_mul_f32_e64 v83, |v83|, s84
	v_exp_f32_e32 v83, v83
	v_min_f32_e32 v84, 0, v84
	v_add_f32_e32 v83, 1.0, v83
	v_log_f32_e32 v83, v83
	s_nop 0
	v_fmac_f32_e32 v84, 0xbf317218, v83
	v_fmac_f32_e32 v238, 0x3d800000, v84
	v_mul_f32_e32 v83, 0x3fb8aa3b, v238
	v_exp_f32_e32 v83, v83
	v_lshlrev_b32_e32 v84, 16, v207
	v_mul_f32_e32 v235, v83, v84
	v_cvt_pk_bf16_f32 v84, v235, s0
	ds_write_b16 v158, v84 offset:1728
	ds_read_b128 v[186:189], v172 offset:47104
	ds_read_b128 v[252:255], v172 offset:47120
	v_mov_b32_e32 v84, v98
	v_rcp_f32_e32 v83, v83
	s_waitcnt lgkmcnt(2)
	v_dot2c_f32_bf16_e32 v84, v178, v99
	v_dot2c_f32_bf16_e32 v84, v179, v100
	v_dot2c_f32_bf16_e32 v84, v180, v101
	v_dot2c_f32_bf16_e32 v84, v181, v102
	v_dot2c_f32_bf16_e32 v84, v182, v103
	v_dot2c_f32_bf16_e32 v84, v183, v104
	v_dot2c_f32_bf16_e32 v84, v184, v105
	v_dot2c_f32_bf16_e32 v84, v185, v106
	s_nop 2
	v_max_f32_e32 v85, v84, v84
	v_mul_f32_e64 v84, |v84|, s84
	v_exp_f32_e32 v84, v84
	v_min_f32_e32 v85, 0, v85
	v_add_f32_e32 v84, 1.0, v84
	v_log_f32_e32 v84, v84
	s_nop 0
	v_fmac_f32_e32 v85, 0xbf317218, v84
	v_fmac_f32_e32 v238, 0x3d800000, v85
	v_mul_f32_e32 v84, 0x3fb8aa3b, v238
	v_exp_f32_e32 v84, v84
	v_lshlrev_b32_e32 v85, 16, v219
	v_mul_f32_e32 v236, v84, v85
	v_cvt_pk_bf16_f32 v85, v236, s0
	ds_write_b16 v158, v85 offset:1872
	v_mov_b32_e32 v85, v98
	v_rcp_f32_e32 v84, v84
	s_waitcnt lgkmcnt(0)
	v_dot2c_f32_bf16_e32 v85, v186, v99
	v_dot2c_f32_bf16_e32 v85, v187, v100
	v_dot2c_f32_bf16_e32 v85, v188, v101
	v_dot2c_f32_bf16_e32 v85, v189, v102
	v_dot2c_f32_bf16_e32 v85, v252, v103
	v_dot2c_f32_bf16_e32 v85, v253, v104
	v_dot2c_f32_bf16_e32 v85, v254, v105
	v_dot2c_f32_bf16_e32 v85, v255, v106
	s_nop 2
	v_max_f32_e32 v86, v85, v85
	v_mul_f32_e64 v85, |v85|, s84
	v_exp_f32_e32 v85, v85
	v_min_f32_e32 v86, 0, v86
	v_add_f32_e32 v85, 1.0, v85
	v_log_f32_e32 v85, v85
	s_nop 0
	v_fmac_f32_e32 v86, 0xbf317218, v85
	v_fmac_f32_e32 v238, 0x3d800000, v86
	v_mul_f32_e32 v85, 0x3fb8aa3b, v238
	v_exp_f32_e32 v86, v85
	v_lshlrev_b32_e32 v85, 16, v220
	v_mul_f32_e32 v237, v86, v85
	v_cvt_pk_bf16_f32 v239, v237, s0
	ds_write_b16 v158, v239 offset:2016
	ds_write2st64_b32 v132, v86, v238 offset0:180 offset1:200
	v_and_b32_e32 v239, 0xffff0000, v224
	v_lshlrev_b32_e32 v238, 16, v224
	v_pk_mul_f32 v[48:49], v[48:49], v[238:239]
	v_and_b32_e32 v239, 0xffff0000, v223
	v_cvt_pk_bf16_f32 v238, v48, s0
	ds_write_b16 v156, v238 offset:9216
	v_cvt_pk_bf16_f32 v238, v49, s0
	ds_write_b16 v158, v238 offset:9216
	v_lshlrev_b32_e32 v238, 16, v223
	v_pk_mul_f32 v[48:49], v[48:49], v[86:87] op_sel_hi:[1,0]
	v_pk_mul_f32 v[50:51], v[50:51], v[238:239]
	v_cvt_pk_bf16_f32 v48, v48, v49
	v_cvt_pk_bf16_f32 v49, v50, s0
	ds_write_b16 v158, v49 offset:9360
	v_cvt_pk_bf16_f32 v49, v51, s0
	v_pk_mul_f32 v[50:51], v[50:51], v[86:87] op_sel_hi:[1,0]
	ds_write_b16 v158, v49 offset:9504
	v_cvt_pk_bf16_f32 v49, v50, v51
	v_and_b32_e32 v51, 0xffff0000, v222
	v_lshlrev_b32_e32 v50, 16, v222
	v_pk_mul_f32 v[50:51], v[52:53], v[50:51]
	v_and_b32_e32 v53, 0xffff0000, v221
	v_cvt_pk_bf16_f32 v52, v50, s0
	ds_write_b16 v158, v52 offset:9648
	v_cvt_pk_bf16_f32 v52, v51, s0
	ds_write_b16 v158, v52 offset:9792
	v_lshlrev_b32_e32 v52, 16, v221
	v_pk_mul_f32 v[50:51], v[50:51], v[86:87] op_sel_hi:[1,0]
	v_pk_mul_f32 v[52:53], v[54:55], v[52:53]
	v_cvt_pk_bf16_f32 v50, v50, v51
	v_cvt_pk_bf16_f32 v51, v52, s0
	ds_write_b16 v158, v51 offset:9936
	v_cvt_pk_bf16_f32 v51, v53, s0
	v_pk_mul_f32 v[52:53], v[52:53], v[86:87] op_sel_hi:[1,0]
	ds_write_b16 v158, v51 offset:10080
	v_cvt_pk_bf16_f32 v51, v52, v53
	v_and_b32_e32 v53, 0xffff0000, v79
	v_lshlrev_b32_e32 v52, 16, v79
	v_pk_mul_f32 v[52:53], v[56:57], v[52:53]
	v_and_b32_e32 v55, 0xffff0000, v77
	v_cvt_pk_bf16_f32 v54, v52, s0
	ds_write_b16 v158, v54 offset:10224
	v_cvt_pk_bf16_f32 v54, v53, s0
	ds_write_b16 v158, v54 offset:10368
	v_lshlrev_b32_e32 v54, 16, v77
	v_pk_mul_f32 v[52:53], v[52:53], v[86:87] op_sel_hi:[1,0]
	v_pk_mul_f32 v[54:55], v[58:59], v[54:55]
	v_cvt_pk_bf16_f32 v52, v52, v53
	v_cvt_pk_bf16_f32 v53, v54, s0
	ds_write_b16 v158, v53 offset:10512
	v_cvt_pk_bf16_f32 v53, v55, s0
	v_pk_mul_f32 v[54:55], v[54:55], v[86:87] op_sel_hi:[1,0]
	ds_write_b16 v158, v53 offset:10656
	v_cvt_pk_bf16_f32 v53, v54, v55
	v_and_b32_e32 v55, 0xffff0000, v75
	v_lshlrev_b32_e32 v54, 16, v75
	v_rcp_f32_e32 v85, v86
	v_pk_mul_f32 v[54:55], v[82:83], v[54:55]
	v_and_b32_e32 v57, 0xffff0000, v73
	v_cvt_pk_bf16_f32 v56, v54, s0
	ds_write_b16 v158, v56 offset:10800
	v_cvt_pk_bf16_f32 v56, v55, s0
	ds_write_b16 v158, v56 offset:10944
	v_lshlrev_b32_e32 v56, 16, v73
	v_pk_mul_f32 v[54:55], v[54:55], v[86:87] op_sel_hi:[1,0]
	v_pk_mul_f32 v[56:57], v[84:85], v[56:57]
	v_cvt_pk_bf16_f32 v54, v54, v55
	v_cvt_pk_bf16_f32 v55, v56, s0
	ds_write_b16 v158, v55 offset:11088
	v_cvt_pk_bf16_f32 v55, v57, s0
	v_pk_mul_f32 v[56:57], v[56:57], v[86:87] op_sel_hi:[1,0]
	ds_write_b16 v158, v55 offset:11232
	v_cvt_pk_bf16_f32 v55, v56, v57
	v_add_u32_e32 v56, v133, v63
	ds_write_b128 v56, v[48:51] offset:18432
	ds_write_b128 v56, v[52:55] offset:18448
	s_waitcnt vmcnt(2)
; #define LAS __attribute__((address_space(3)))
; DI unsigned short f2bf(float x) { return (unsigned short)(pk2(x, 0.f) & 0xffffu); }
; #define BAR_LDS() do { asm volatile("s_waitcnt lgkmcnt(0)" ::: "memory"); __builtin_amdgcn_s_barrier(); asm volatile("" ::: "memory"); } while (0)
; DI float fexp_(float x) { return __builtin_amdgcn_exp2f(1.4426950408889634f * x); }
; DI void gla_pass1(LAS unsigned char* lds, const Args& A, const bf16* proj, bf16* scratch, bf16* QS, bf16* HT, float* DD, int T, int b, int h, int k, int tid_in) {
;     ...
;         for (int q = 0; q < 4; ++q) { const int idx = tl + 256 * q, tk = idx & 63, v0 = (idx >> 6) * 8;
; #pragma unroll
;             for (int e = 0; e < 8; ++e) { const unsigned w = vraw[q][e >> 1]; *(LAS unsigned short*)(L + GL_VT + (v0 + e) * GL_P + tk * 2) = (unsigned short)((e & 1) ? (w >> 16) : (w & 0xffffu)); } }
;         BAR_LDS();
;         {   const LAS float* CL = (const LAS float*)(L + GL_CL) + d; const float c0 = CL[0], c1 = CL[64], c2 = CL[128], c3 = CL[192];
;             const float off = carry + ((c > 0) ? c0 : 0.f) + ((c > 1) ? c1 : 0.f) + ((c > 2) ? c2 : 0.f);
;             carry += (c0 + c1) + (c2 + c3);
;             const float eo = fexp_(off);
; #pragma unroll
;             for (int i = 0; i < 16; ++i) QS[GLA_ROW(it * 64 + c * 16 + i) * 512 + dir * 256 + h * 64 + d] = f2bf(qdv[i] * eo); }
	ds_write_b16 v173, v0 offset:27648
	ds_write_b16_d16_hi v173, v0 offset:27792
	ds_write_b16 v173, v1 offset:27936
	ds_write_b16_d16_hi v173, v1 offset:28080
	ds_write_b16 v173, v2 offset:28224
	ds_write_b16_d16_hi v173, v2 offset:28368
	ds_write_b16 v173, v3 offset:28512
	ds_write_b16_d16_hi v173, v3 offset:28656
	s_waitcnt vmcnt(1)
	ds_write_b16 v174, v4 offset:27648
	ds_write_b16_d16_hi v174, v4 offset:27792
	ds_write_b16 v174, v5 offset:27936
	ds_write_b16_d16_hi v174, v5 offset:28080
	ds_write_b16 v174, v6 offset:28224
	ds_write_b16_d16_hi v174, v6 offset:28368
	ds_write_b16 v174, v7 offset:28512
	ds_write_b16_d16_hi v175, v7 offset:27648
	ds_write_b16 v190, v8 offset:27648
	ds_write_b16_d16_hi v190, v8 offset:27792
	ds_write_b16 v190, v9 offset:27936
	ds_write_b16_d16_hi v190, v9 offset:28080
	ds_write_b16 v190, v10 offset:28224
	ds_write_b16_d16_hi v190, v10 offset:28368
	ds_write_b16 v190, v11 offset:28512
	ds_write_b16_d16_hi v191, v11 offset:27648
	s_waitcnt vmcnt(0)
	ds_write_b16 v192, v12 offset:27648
	ds_write_b16_d16_hi v192, v12 offset:27792
	ds_write_b16 v192, v13 offset:27936
	ds_write_b16_d16_hi v192, v13 offset:28080
	ds_write_b16 v192, v14 offset:28224
	ds_write_b16_d16_hi v192, v14 offset:28368
	ds_write_b16 v192, v15 offset:28512
	ds_write_b16_d16_hi v193, v15 offset:27648
	s_waitcnt lgkmcnt(0)
	s_barrier
	ds_read2st64_b32 v[82:83], v194 offset0:200 offset1:201
	ds_read2st64_b32 v[84:85], v194 offset0:202 offset1:203
	s_waitcnt lgkmcnt(1)
	v_cndmask_b32_e64 v48, v82, 0, s[40:41]
	v_add_f32_e32 v48, v126, v48
	v_cndmask_b32_e64 v49, 0, v83, s[42:43]
	v_add_f32_e32 v48, v48, v49
	s_waitcnt lgkmcnt(0)
	v_cndmask_b32_e64 v49, 0, v84, s[44:45]
	v_add_f32_e32 v48, v48, v49
	v_mul_f32_e32 v48, 0x3fb8aa3b, v48
	v_exp_f32_e32 v48, v48
	v_or_b32_e32 v49, s0, v91
	v_mul_f32_e32 v50, v233, v48
	v_cvt_pk_bf16_f32 v52, v50, s0
	v_sub_u32_e32 v50, 0x3ff, v49
	v_cndmask_b32_e32 v50, v50, v49, vcc
	v_ashrrev_i32_e32 v51, 31, v50
	v_lshl_add_u64 v[50:51], s[76:77], 0, v[50:51]
	v_lshlrev_b64 v[50:51], 10, v[50:51]
	v_lshl_add_u64 v[50:51], v[70:71], 0, v[50:51]
	global_store_short v[50:51], v52, off
	v_subrev_u32_e32 v51, s0, v92
	v_or_b32_e32 v52, 1, v49
	v_cndmask_b32_e32 v52, v51, v52, vcc
	v_ashrrev_i32_e32 v53, 31, v52
	v_lshl_add_u64 v[52:53], s[76:77], 0, v[52:53]
	v_mul_f32_e32 v50, v231, v48
	v_lshlrev_b64 v[52:53], 10, v[52:53]
	v_cvt_pk_bf16_f32 v50, v50, s0
	v_lshl_add_u64 v[52:53], v[70:71], 0, v[52:53]
	global_store_short v[52:53], v50, off
	v_mul_f32_e32 v50, v87, v48
	v_cvt_pk_bf16_f32 v52, v50, s0
	v_subrev_u32_e32 v50, s0, v93
	v_or_b32_e32 v51, 2, v49
	v_cndmask_b32_e32 v50, v50, v51, vcc
	v_ashrrev_i32_e32 v51, 31, v50
	v_lshl_add_u64 v[50:51], s[76:77], 0, v[50:51]
	v_lshlrev_b64 v[50:51], 10, v[50:51]
	v_lshl_add_u64 v[50:51], v[70:71], 0, v[50:51]
	global_store_short v[50:51], v52, off
	v_mul_f32_e32 v50, v88, v48
	v_cvt_pk_bf16_f32 v52, v50, s0
	v_subrev_u32_e32 v50, s0, v94
	v_or_b32_e32 v51, 3, v49
	v_cndmask_b32_e32 v50, v50, v51, vcc
	v_ashrrev_i32_e32 v51, 31, v50
	v_lshl_add_u64 v[50:51], s[76:77], 0, v[50:51]
	v_lshlrev_b64 v[50:51], 10, v[50:51]
	v_lshl_add_u64 v[50:51], v[70:71], 0, v[50:51]
	global_store_short v[50:51], v52, off
	v_mul_f32_e32 v50, v89, v48
	v_cvt_pk_bf16_f32 v52, v50, s0
	v_subrev_u32_e32 v50, s0, v95
	v_or_b32_e32 v51, 4, v49
	v_cndmask_b32_e32 v50, v50, v51, vcc
	v_ashrrev_i32_e32 v51, 31, v50
	v_lshl_add_u64 v[50:51], s[76:77], 0, v[50:51]
	v_lshlrev_b64 v[50:51], 10, v[50:51]
	v_lshl_add_u64 v[50:51], v[70:71], 0, v[50:51]
	global_store_short v[50:51], v52, off
	v_mul_f32_e32 v50, v225, v48
	v_cvt_pk_bf16_f32 v52, v50, s0
	v_subrev_u32_e32 v50, s0, v96
	v_or_b32_e32 v51, 5, v49
	v_cndmask_b32_e32 v50, v50, v51, vcc
	v_ashrrev_i32_e32 v51, 31, v50
	v_lshl_add_u64 v[50:51], s[76:77], 0, v[50:51]
	v_lshlrev_b64 v[50:51], 10, v[50:51]
	v_lshl_add_u64 v[50:51], v[70:71], 0, v[50:51]
	global_store_short v[50:51], v52, off
	v_mul_f32_e32 v50, v226, v48
	v_cvt_pk_bf16_f32 v52, v50, s0
	v_subrev_u32_e32 v50, s0, v97
	v_or_b32_e32 v51, 6, v49
	v_cndmask_b32_e32 v50, v50, v51, vcc
	v_ashrrev_i32_e32 v51, 31, v50
	v_lshl_add_u64 v[50:51], s[76:77], 0, v[50:51]
	v_lshlrev_b64 v[50:51], 10, v[50:51]
	v_lshl_add_u64 v[50:51], v[70:71], 0, v[50:51]
	global_store_short v[50:51], v52, off
	v_mul_f32_e32 v50, v227, v48
	v_cvt_pk_bf16_f32 v52, v50, s0
	v_subrev_u32_e32 v50, s0, v108
	v_or_b32_e32 v51, 7, v49
	v_cndmask_b32_e32 v50, v50, v51, vcc
	v_ashrrev_i32_e32 v51, 31, v50
	v_lshl_add_u64 v[50:51], s[76:77], 0, v[50:51]
	v_lshlrev_b64 v[50:51], 10, v[50:51]
	v_lshl_add_u64 v[50:51], v[70:71], 0, v[50:51]
	global_store_short v[50:51], v52, off
	v_mul_f32_e32 v50, v228, v48
	v_cvt_pk_bf16_f32 v52, v50, s0
	v_subrev_u32_e32 v50, s0, v110
	v_or_b32_e32 v51, 8, v49
	v_cndmask_b32_e32 v50, v50, v51, vcc
	v_ashrrev_i32_e32 v51, 31, v50
	v_lshl_add_u64 v[50:51], s[76:77], 0, v[50:51]
	v_lshlrev_b64 v[50:51], 10, v[50:51]
	v_lshl_add_u64 v[50:51], v[70:71], 0, v[50:51]
	global_store_short v[50:51], v52, off
	v_mul_f32_e32 v50, v229, v48
	v_cvt_pk_bf16_f32 v52, v50, s0
	v_subrev_u32_e32 v50, s0, v111
	v_or_b32_e32 v51, 9, v49
	v_cndmask_b32_e32 v50, v50, v51, vcc
	v_ashrrev_i32_e32 v51, 31, v50
	v_lshl_add_u64 v[50:51], s[76:77], 0, v[50:51]
	v_lshlrev_b64 v[50:51], 10, v[50:51]
	v_lshl_add_u64 v[50:51], v[70:71], 0, v[50:51]
	global_store_short v[50:51], v52, off
	v_mul_f32_e32 v50, v230, v48
	v_cvt_pk_bf16_f32 v52, v50, s0
	v_subrev_u32_e32 v50, s0, v112
	v_or_b32_e32 v51, 10, v49
	v_cndmask_b32_e32 v50, v50, v51, vcc
	v_ashrrev_i32_e32 v51, 31, v50
	v_lshl_add_u64 v[50:51], s[76:77], 0, v[50:51]
; #define LAS __attribute__((address_space(3)))
; DI void gla_pass1(LAS unsigned char* lds, const Args& A, const bf16* proj, bf16* scratch, bf16* QS, bf16* HT, float* DD, int T, int b, int h, int k, int tid_in) {
;     ...
;             for (int i = 0; i < 16; ++i) QS[GLA_ROW(it * 64 + c * 16 + i) * 512 + dir * 256 + h * 64 + d] = f2bf(qdv[i] * eo); }
; #pragma unroll
;         for (int cc = 0; cc < 4; ++cc) {
;             const int trow = cc * 16 + l15;
;             f32x4 X = (f32x4){0.f, 0.f, 0.f, 0.f};
; #pragma unroll
;             for (int ks = 0; ks < 2; ++ks) { const bf16x8 ki = *(const LAS bf16x8*)(L + GL_KI + trow * GL_P + (ks * 32 + 8 * g) * 2), qd = *(const LAS bf16x8*)(L + GL_QD + trow * GL_P + (ks * 32 + 8 * g) * 2);
;                 X = MFMA32(ki, qd, X); }
; #pragma unroll
;             for (int r = 0; r < 4; ++r) if (4 * g + r > l15) X[r] = 0.f;
;             u32x2 pp; pp.x = pk2(X[0], X[1]); pp.y = pk2(X[2], X[3]);
;             const s16x4 P = __builtin_bit_cast(s16x4, pp);
;             s16x4 vt[2]; f32x4 o[2];
; #pragma unroll
;             for (int nt = 0; nt < 2; ++nt) { vt[nt] = *(const LAS s16x4*)(L + GL_VT + (vs + 16 * nt + l15) * GL_P + (cc * 16 + 4 * g) * 2);
;                 o[nt] = MFMA16(P, vt[nt], ((f32x4){0.f, 0.f, 0.f, 0.f})); }
; #pragma unroll
;             for (int ks = 0; ks < 2; ++ks) {
;                 const u32x2 qlo = *(const LAS u32x2*)(L + GL_QD + trow * GL_P + (32 * ks + 4 * g) * 2), qhi = *(const LAS u32x2*)(L + GL_QD + trow * GL_P + (32 * ks + 16 + 4 * g) * 2);
;                 const u32x4 qq = (u32x4){qlo.x, qlo.y, qhi.x, qhi.y}; const bf16x8 qa = __builtin_bit_cast(bf16x8, qq);
; #pragma unroll
;                 for (int nt = 0; nt < 2; ++nt) { const f32x4 s0 = S[2 * ks][nt], s1 = S[2 * ks + 1][nt];
;                     const u32x4 sw = (u32x4){pk2(s0[0], s0[1]), pk2(s0[2], s0[3]), pk2(s1[0], s1[1]), pk2(s1[2], s1[3])};
;                     o[nt] = MFMA32(qa, __builtin_bit_cast(bf16x8, sw), o[nt]); } }
; #pragma unroll
;             for (int r = 0; r < 4; ++r) { LAS unsigned short* op = (LAS unsigned short*)(L + GL_OB + (cc * 16 + 4 * g + r) * GL_OBP + (vs + l15) * 2); op[0] = f2bf(o[0][r]); op[16] = f2bf(o[1][r]); }
; #pragma unroll
;             for (int mt = 0; mt < 4; ++mt) { const f32x4 dec = *(const LAS f32x4*)(L + GL_DEC + (cc * 64 + 16 * mt + 4 * g) * 4);
	v_lshlrev_b64 v[50:51], 10, v[50:51]
	v_lshl_add_u64 v[50:51], v[70:71], 0, v[50:51]
	global_store_short v[50:51], v52, off
	v_mul_f32_e32 v50, v232, v48
	v_cvt_pk_bf16_f32 v52, v50, s0
	v_subrev_u32_e32 v50, s0, v114
	v_or_b32_e32 v51, 11, v49
	v_cndmask_b32_e32 v50, v50, v51, vcc
	v_ashrrev_i32_e32 v51, 31, v50
	v_lshl_add_u64 v[50:51], s[76:77], 0, v[50:51]
	v_lshlrev_b64 v[50:51], 10, v[50:51]
	v_lshl_add_u64 v[50:51], v[70:71], 0, v[50:51]
	global_store_short v[50:51], v52, off
	v_mul_f32_e32 v50, v234, v48
	v_cvt_pk_bf16_f32 v52, v50, s0
	v_subrev_u32_e32 v50, s0, v115
	v_or_b32_e32 v51, 12, v49
	v_cndmask_b32_e32 v50, v50, v51, vcc
	v_ashrrev_i32_e32 v51, 31, v50
	v_lshl_add_u64 v[50:51], s[76:77], 0, v[50:51]
	v_lshlrev_b64 v[50:51], 10, v[50:51]
	v_lshl_add_u64 v[50:51], v[70:71], 0, v[50:51]
	global_store_short v[50:51], v52, off
	v_mul_f32_e32 v50, v235, v48
	v_cvt_pk_bf16_f32 v52, v50, s0
	v_subrev_u32_e32 v50, s0, v117
	v_or_b32_e32 v51, 13, v49
	v_cndmask_b32_e32 v50, v50, v51, vcc
	v_ashrrev_i32_e32 v51, 31, v50
	v_lshl_add_u64 v[50:51], s[76:77], 0, v[50:51]
	v_lshlrev_b64 v[50:51], 10, v[50:51]
	v_lshl_add_u64 v[50:51], v[70:71], 0, v[50:51]
	global_store_short v[50:51], v52, off
	v_mul_f32_e32 v50, v236, v48
	v_cvt_pk_bf16_f32 v52, v50, s0
	v_subrev_u32_e32 v50, s0, v118
	v_or_b32_e32 v51, 14, v49
	v_cndmask_b32_e32 v50, v50, v51, vcc
	v_ashrrev_i32_e32 v51, 31, v50
	v_lshl_add_u64 v[50:51], s[76:77], 0, v[50:51]
	v_lshlrev_b64 v[50:51], 10, v[50:51]
	v_lshl_add_u64 v[50:51], v[70:71], 0, v[50:51]
	v_mul_f32_e32 v48, v237, v48
	global_store_short v[50:51], v52, off
	v_cvt_pk_bf16_f32 v50, v48, s0
	v_subrev_u32_e32 v48, s0, v120
	v_or_b32_e32 v49, 15, v49
	v_cndmask_b32_e32 v48, v48, v49, vcc
	v_ashrrev_i32_e32 v49, 31, v48
	v_lshl_add_u64 v[48:49], s[76:77], 0, v[48:49]
	v_lshlrev_b64 v[48:49], 10, v[48:49]
	v_lshl_add_u64 v[48:49], v[70:71], 0, v[48:49]
	global_store_short v[48:49], v50, off
	ds_read_b128 v[48:51], v203 offset:9216
	ds_read_b128 v[52:55], v203
	s_waitcnt lgkmcnt(0)
	v_mfma_f32_16x16x32_bf16 v[48:51], v[48:51], v[52:55], 0
	ds_read_b128 v[52:55], v203 offset:9280
	ds_read_b128 v[56:59], v203 offset:64
	v_add_u32_e32 v226, v139, v144
	ds_read_b64 v[86:87], v204 offset:27648
	ds_read_b64 v[88:89], v204 offset:29952
	s_waitcnt lgkmcnt(2)
	v_mfma_f32_16x16x32_bf16 v[48:51], v[52:55], v[56:59], v[48:51]
	v_mov_b32_e32 v52, s13
	ds_read2_b64 v[56:59], v226 offset1:4
	v_cvt_pk_bf16_f32 v228, v28, v29
	v_cvt_pk_bf16_f32 v229, v30, v31
	s_nop 3
	v_cndmask_b32_e64 v52, v48, v52, s[46:47]
	v_cndmask_b32_e64 v48, v52, v48, s[48:49]
	v_cndmask_b32_e64 v49, 0, v49, s[48:49]
	v_cndmask_b32_e64 v50, v50, 0, s[50:51]
	v_cndmask_b32_e64 v51, v51, 0, s[52:53]
	v_cvt_pk_bf16_f32 v52, v48, v49
	v_cvt_pk_bf16_f32 v53, v50, v51
	v_cvt_pk_bf16_f32 v230, v20, v21
	v_cvt_pk_bf16_f32 v231, v22, v23
	s_waitcnt lgkmcnt(2)
	v_mfma_f32_16x16x16_bf16 v[48:51], v[52:53], v[86:87], 0
	v_add_u32_e32 v225, v90, v138
	v_add_u32_e32 v227, 0x800, v226
	s_waitcnt lgkmcnt(1)
	v_mfma_f32_16x16x16_bf16 v[52:55], v[52:53], v[88:89], 0
	s_waitcnt lgkmcnt(0)
	v_mfma_f32_16x16x32_bf16 v[48:51], v[56:59], v[228:231], v[48:51]
	v_cvt_pk_bf16_f32 v228, v24, v25
	v_cvt_pk_bf16_f32 v229, v26, v27
	v_cvt_pk_bf16_f32 v230, v16, v17
	v_cvt_pk_bf16_f32 v231, v18, v19
	s_nop 1
	v_mfma_f32_16x16x32_bf16 v[52:55], v[56:59], v[228:231], v[52:55]
	ds_read2_b64 v[56:59], v226 offset0:8 offset1:12
	v_cvt_pk_bf16_f32 v228, v36, v37
	v_cvt_pk_bf16_f32 v229, v38, v39
	v_cvt_pk_bf16_f32 v230, v40, v41
	v_cvt_pk_bf16_f32 v231, v42, v43
	s_waitcnt lgkmcnt(0)
	s_nop 0
	v_mfma_f32_16x16x32_bf16 v[48:51], v[56:59], v[228:231], v[48:51]
	v_cvt_pk_bf16_f32 v228, v32, v33
	v_cvt_pk_bf16_f32 v229, v34, v35
	v_cvt_pk_bf16_f32 v230, v44, v45
	v_cvt_pk_bf16_f32 v231, v46, v47
	s_nop 3
	v_cvt_pk_bf16_f32 v48, v48, s0
	ds_write_b16 v145, v48 offset:52224
	v_mfma_f32_16x16x32_bf16 v[52:55], v[56:59], v[228:231], v[52:55]
	s_nop 7
	v_cvt_pk_bf16_f32 v48, v52, s0
	ds_write_b16 v145, v48 offset:52256
	v_cvt_pk_bf16_f32 v48, v49, s0
	ds_write_b16 v145, v48 offset:52496
	v_cvt_pk_bf16_f32 v48, v53, s0
	ds_write_b16 v145, v48 offset:52528
	v_cvt_pk_bf16_f32 v48, v50, s0
	ds_write_b16 v195, v48 offset:52224
	v_cvt_pk_bf16_f32 v48, v54, s0
	ds_write_b16 v195, v48 offset:52256
	v_cvt_pk_bf16_f32 v48, v51, s0
	ds_write_b16 v195, v48 offset:52496
	v_cvt_pk_bf16_f32 v48, v55, s0
	ds_write_b16 v195, v48 offset:52528
	ds_read_b128 v[48:51], v225 offset:46080
	ds_read_b64 v[52:53], v226 offset:18432
	s_waitcnt lgkmcnt(1)
	v_pk_mul_f32 v[28:29], v[28:29], v[48:49]
	v_pk_mul_f32 v[30:31], v[30:31], v[50:51]
	v_pk_mul_f32 v[24:25], v[24:25], v[48:49]
	v_pk_mul_f32 v[26:27], v[26:27], v[50:51]
	ds_read_b128 v[48:51], v225 offset:46144
	ds_read_b64 v[56:57], v226 offset:20736
	s_waitcnt lgkmcnt(2)
	v_mfma_f32_16x16x16_bf16 v[28:31], v[52:53], v[86:87], v[28:31]
	s_waitcnt lgkmcnt(1)
	v_pk_mul_f32 v[20:21], v[20:21], v[48:49]
	v_pk_mul_f32 v[22:23], v[22:23], v[50:51]
	v_pk_mul_f32 v[16:17], v[16:17], v[48:49]
	v_pk_mul_f32 v[18:19], v[18:19], v[50:51]
	v_mfma_f32_16x16x16_bf16 v[24:27], v[52:53], v[88:89], v[24:27]
	s_waitcnt lgkmcnt(0)
	v_mfma_f32_16x16x16_bf16 v[52:55], v[56:57], v[86:87], v[20:23]
	v_mfma_f32_16x16x16_bf16 v[56:59], v[56:57], v[88:89], v[16:19]
	s_nop 2
	ds_read_b128 v[16:19], v225 offset:46208
	ds_read_b64 v[48:49], v226 offset:23040
	s_waitcnt lgkmcnt(1)
	v_pk_mul_f32 v[20:21], v[36:37], v[16:17]
	v_pk_mul_f32 v[22:23], v[38:39], v[18:19]
	v_pk_mul_f32 v[16:17], v[32:33], v[16:17]
	v_pk_mul_f32 v[18:19], v[34:35], v[18:19]
	s_waitcnt lgkmcnt(0)
; #define LAS __attribute__((address_space(3)))
; DI void gla_pass1(LAS unsigned char* lds, const Args& A, const bf16* proj, bf16* scratch, bf16* QS, bf16* HT, float* DD, int T, int b, int h, int k, int tid_in) {
;     ...
;         for (int cc = 0; cc < 4; ++cc) {
;             const int trow = cc * 16 + l15;
;             f32x4 X = (f32x4){0.f, 0.f, 0.f, 0.f};
; #pragma unroll
;             for (int ks = 0; ks < 2; ++ks) { const bf16x8 ki = *(const LAS bf16x8*)(L + GL_KI + trow * GL_P + (ks * 32 + 8 * g) * 2), qd = *(const LAS bf16x8*)(L + GL_QD + trow * GL_P + (ks * 32 + 8 * g) * 2);
;                 X = MFMA32(ki, qd, X); }
; #pragma unroll
;             for (int r = 0; r < 4; ++r) if (4 * g + r > l15) X[r] = 0.f;
;             u32x2 pp; pp.x = pk2(X[0], X[1]); pp.y = pk2(X[2], X[3]);
;             const s16x4 P = __builtin_bit_cast(s16x4, pp);
;             s16x4 vt[2]; f32x4 o[2];
; #pragma unroll
;             for (int nt = 0; nt < 2; ++nt) { vt[nt] = *(const LAS s16x4*)(L + GL_VT + (vs + 16 * nt + l15) * GL_P + (cc * 16 + 4 * g) * 2);
;                 o[nt] = MFMA16(P, vt[nt], ((f32x4){0.f, 0.f, 0.f, 0.f})); }
; #pragma unroll
;             for (int ks = 0; ks < 2; ++ks) {
;                 const u32x2 qlo = *(const LAS u32x2*)(L + GL_QD + trow * GL_P + (32 * ks + 4 * g) * 2), qhi = *(const LAS u32x2*)(L + GL_QD + trow * GL_P + (32 * ks + 16 + 4 * g) * 2);
;                 const u32x4 qq = (u32x4){qlo.x, qlo.y, qhi.x, qhi.y}; const bf16x8 qa = __builtin_bit_cast(bf16x8, qq);
; #pragma unroll
;                 for (int nt = 0; nt < 2; ++nt) { const f32x4 s0 = S[2 * ks][nt], s1 = S[2 * ks + 1][nt];
;                     const u32x4 sw = (u32x4){pk2(s0[0], s0[1]), pk2(s0[2], s0[3]), pk2(s1[0], s1[1]), pk2(s1[2], s1[3])};
;                     o[nt] = MFMA32(qa, __builtin_bit_cast(bf16x8, sw), o[nt]); } }
; #pragma unroll
;             for (int r = 0; r < 4; ++r) { LAS unsigned short* op = (LAS unsigned short*)(L + GL_OB + (cc * 16 + 4 * g + r) * GL_OBP + (vs + l15) * 2); op[0] = f2bf(o[0][r]); op[16] = f2bf(o[1][r]); }
; #pragma unroll
;             for (int mt = 0; mt < 4; ++mt) { const f32x4 dec = *(const LAS f32x4*)(L + GL_DEC + (cc * 64 + 16 * mt + 4 * g) * 4);
;                 const s16x4 kd = *(const LAS s16x4*)(L + GL_KDT + (16 * mt + l15) * GL_P + (cc * 16 + 4 * g) * 2);
; #pragma unroll
	v_mfma_f32_16x16x16_bf16 v[36:39], v[48:49], v[86:87], v[20:23]
	v_mfma_f32_16x16x16_bf16 v[48:51], v[48:49], v[88:89], v[16:19]
	s_nop 2
	ds_read_b128 v[16:19], v225 offset:46272
	ds_read_b64 v[32:33], v226 offset:25344
	s_waitcnt lgkmcnt(1)
	v_pk_mul_f32 v[20:21], v[40:41], v[16:17]
	v_pk_mul_f32 v[22:23], v[42:43], v[18:19]
	v_pk_mul_f32 v[16:17], v[44:45], v[16:17]
	v_pk_mul_f32 v[18:19], v[46:47], v[18:19]
	s_waitcnt lgkmcnt(0)
	v_mfma_f32_16x16x16_bf16 v[40:43], v[32:33], v[86:87], v[20:23]
	v_mfma_f32_16x16x16_bf16 v[44:47], v[32:33], v[88:89], v[16:19]
	s_nop 2
	ds_read2_b64 v[16:19], v227 offset0:32 offset1:36
	ds_read_b64 v[86:87], v204 offset:29984
	ds_read_b64 v[88:89], v204 offset:27680
	ds_read_b128 v[20:23], v203 offset:2368
	ds_read_b128 v[32:35], v203 offset:11584
	ds_read_b128 v[228:231], v203 offset:2304
	ds_read_b128 v[232:235], v203 offset:11520
	s_waitcnt lgkmcnt(0)
	v_mfma_f32_16x16x32_bf16 v[228:231], v[232:235], v[228:231], 0
	v_mfma_f32_16x16x32_bf16 v[20:23], v[32:35], v[20:23], v[228:231]
	v_mov_b32_e32 v32, s13
	s_nop 5
	v_cvt_pk_bf16_f32 v228, v28, v29
	v_cvt_pk_bf16_f32 v229, v30, v31
	v_cndmask_b32_e64 v32, v20, v32, s[46:47]
	v_cndmask_b32_e64 v20, v32, v20, s[48:49]
	v_cndmask_b32_e64 v21, 0, v21, s[48:49]
	v_cndmask_b32_e64 v22, v22, 0, s[50:51]
	v_cndmask_b32_e64 v23, v23, 0, s[52:53]
	v_cvt_pk_bf16_f32 v32, v20, v21
	v_cvt_pk_bf16_f32 v33, v22, v23
	v_cvt_pk_bf16_f32 v230, v52, v53
	v_cvt_pk_bf16_f32 v231, v54, v55
	v_mfma_f32_16x16x16_bf16 v[20:23], v[32:33], v[88:89], 0
	v_mfma_f32_16x16x16_bf16 v[32:35], v[32:33], v[86:87], 0
	v_mfma_f32_16x16x32_bf16 v[20:23], v[16:19], v[228:231], v[20:23]
	v_cvt_pk_bf16_f32 v228, v24, v25
	v_cvt_pk_bf16_f32 v229, v26, v27
	v_cvt_pk_bf16_f32 v230, v56, v57
	v_cvt_pk_bf16_f32 v231, v58, v59
	s_nop 1
	v_mfma_f32_16x16x32_bf16 v[16:19], v[16:19], v[228:231], v[32:35]
	v_cvt_pk_bf16_f32 v228, v36, v37
	v_cvt_pk_bf16_f32 v229, v38, v39
	v_cvt_pk_bf16_f32 v230, v40, v41
	ds_read2_b64 v[32:35], v227 offset0:40 offset1:44
	v_cvt_pk_bf16_f32 v231, v42, v43
	s_waitcnt lgkmcnt(0)
	s_nop 0
	v_mfma_f32_16x16x32_bf16 v[20:23], v[32:35], v[228:231], v[20:23]
	v_cvt_pk_bf16_f32 v228, v48, v49
	v_cvt_pk_bf16_f32 v229, v50, v51
	v_cvt_pk_bf16_f32 v230, v44, v45
	v_cvt_pk_bf16_f32 v231, v46, v47
	s_nop 3
	v_cvt_pk_bf16_f32 v20, v20, s0
	ds_write_b16 v196, v20 offset:52224
	v_mfma_f32_16x16x32_bf16 v[16:19], v[32:35], v[228:231], v[16:19]
	s_nop 7
	v_cvt_pk_bf16_f32 v16, v16, s0
	ds_write_b16 v196, v16 offset:52256
	v_cvt_pk_bf16_f32 v16, v21, s0
	ds_write_b16 v145, v16 offset:56848
	v_cvt_pk_bf16_f32 v16, v17, s0
	ds_write_b16 v145, v16 offset:56880
	v_cvt_pk_bf16_f32 v16, v22, s0
	ds_write_b16 v145, v16 offset:57120
	v_cvt_pk_bf16_f32 v16, v18, s0
	ds_write_b16 v145, v16 offset:57152
	v_cvt_pk_bf16_f32 v16, v23, s0
	ds_write_b16 v145, v16 offset:57392
	v_cvt_pk_bf16_f32 v16, v19, s0
	ds_write_b16 v145, v16 offset:57424
	ds_read_b128 v[20:23], v225 offset:46336
	ds_read_b64 v[32:33], v198 offset:18432
	s_waitcnt lgkmcnt(1)
	v_pk_mul_f32 v[18:19], v[30:31], v[22:23]
	v_pk_mul_f32 v[16:17], v[28:29], v[20:21]
	v_pk_mul_f32 v[22:23], v[26:27], v[22:23]
	v_pk_mul_f32 v[20:21], v[24:25], v[20:21]
	s_waitcnt lgkmcnt(0)
	v_mfma_f32_16x16x16_bf16 v[16:19], v[32:33], v[88:89], v[16:19]
	v_mfma_f32_16x16x16_bf16 v[20:23], v[32:33], v[86:87], v[20:23]
	ds_read_b128 v[28:31], v225 offset:46400
	ds_read_b64 v[32:33], v198 offset:20736
	s_waitcnt lgkmcnt(1)
	v_pk_mul_f32 v[26:27], v[54:55], v[30:31]
	v_pk_mul_f32 v[24:25], v[52:53], v[28:29]
	v_pk_mul_f32 v[28:29], v[56:57], v[28:29]
	ds_read_b128 v[52:55], v225 offset:46464
	ds_read_b64 v[56:57], v198 offset:23040
	v_pk_mul_f32 v[30:31], v[58:59], v[30:31]
	s_waitcnt lgkmcnt(2)
	v_mfma_f32_16x16x16_bf16 v[24:27], v[32:33], v[88:89], v[24:27]
	s_waitcnt lgkmcnt(1)
	v_pk_mul_f32 v[34:35], v[38:39], v[54:55]
	v_pk_mul_f32 v[38:39], v[50:51], v[54:55]
	v_mfma_f32_16x16x16_bf16 v[28:31], v[32:33], v[86:87], v[28:31]
	v_mul_f32_e64 v32, v36, v52
	v_mul_f32_e64 v33, v37, v53
	v_pk_mul_f32 v[36:37], v[48:49], v[52:53]
	ds_read_b128 v[48:51], v225 offset:46528
	ds_read_b64 v[52:53], v198 offset:25344
	s_waitcnt lgkmcnt(2)
	v_mfma_f32_16x16x16_bf16 v[32:35], v[56:57], v[88:89], v[32:35]
	s_waitcnt lgkmcnt(1)
	v_pk_mul_f32 v[42:43], v[42:43], v[50:51]
	v_pk_mul_f32 v[40:41], v[40:41], v[48:49]
	v_pk_mul_f32 v[46:47], v[46:47], v[50:51]
	v_pk_mul_f32 v[44:45], v[44:45], v[48:49]
	v_mfma_f32_16x16x16_bf16 v[36:39], v[56:57], v[86:87], v[36:39]
	s_waitcnt lgkmcnt(0)
	v_mfma_f32_16x16x16_bf16 v[40:43], v[52:53], v[88:89], v[40:43]
	v_mfma_f32_16x16x16_bf16 v[44:47], v[52:53], v[86:87], v[44:47]
	s_cbranch_scc1 .LBB0_414
; DI void gla_pass1(LAS unsigned char* lds, const Args& A, const bf16* proj, bf16* scratch, bf16* QS, bf16* HT, float* DD, int T, int b, int h, int k, int tid_in) {
;     ...
;             if (cc == 1 && it + 1 < NI) GLA_PREFETCH(it + 1);
	s_add_i32 s4, s0, 64
	v_or_b32_e32 v1, s0, v62
	v_or_b32_e32 v0, s4, v62
	v_sub_u32_e32 v1, 0x3bf, v1
	v_cndmask_b32_e32 v0, v1, v0, vcc
	v_ashrrev_i32_e32 v1, 31, v0
	v_lshl_add_u64 v[2:3], s[76:77], 0, v[0:1]
	v_mov_b64_e32 v[0:1], s[70:71]
	v_mad_u64_u32 v[4:5], s[0:1], v2, s85, v[0:1]
	v_mad_i32_i24 v5, v3, s85, v5
	v_lshl_add_u64 v[2:3], v[4:5], 0, s[12:13]
	v_or_b32_e32 v7, s4, v91
	v_lshl_add_u64 v[12:13], v[2:3], 0, s[74:75]
	v_sub_u32_e32 v2, 0x3ff, v7
	v_cndmask_b32_e32 v2, v2, v7, vcc
	v_ashrrev_i32_e32 v3, 31, v2
	v_lshl_add_u64 v[2:3], s[76:77], 0, v[2:3]
	v_mad_u64_u32 v[4:5], s[0:1], v2, s85, v[64:65]
	v_mad_i32_i24 v5, v3, s85, v5
	v_sub_u32_e32 v2, 0x3fe, v7
	v_or_b32_e32 v3, 1, v7
	v_cndmask_b32_e32 v2, v2, v3, vcc
	v_ashrrev_i32_e32 v3, 31, v2
	v_lshl_add_u64 v[2:3], s[76:77], 0, v[2:3]
	global_load_ushort v107, v[4:5], off offset:3072
	global_load_ushort v178, v[4:5], off offset:3584
	v_mad_u64_u32 v[4:5], s[0:1], v2, s85, v[64:65]
	v_or_b32_e32 v2, 2, v7
	v_mad_i32_i24 v5, v3, s85, v5
	v_sub_u32_e32 v3, 0x3ff, v2
	v_cndmask_b32_e32 v2, v3, v2, vcc
	v_ashrrev_i32_e32 v3, 31, v2
	v_lshl_add_u64 v[2:3], s[76:77], 0, v[2:3]
	global_load_ushort v109, v[4:5], off offset:3072
	global_load_ushort v179, v[4:5], off offset:3584
	v_mad_u64_u32 v[4:5], s[0:1], v2, s85, v[64:65]
	v_or_b32_e32 v2, 3, v7
	v_mad_i32_i24 v5, v3, s85, v5
	v_sub_u32_e32 v3, 0x3ff, v2
	v_cndmask_b32_e32 v2, v3, v2, vcc
	v_ashrrev_i32_e32 v3, 31, v2
	v_lshl_add_u64 v[2:3], s[76:77], 0, v[2:3]
	global_load_ushort v113, v[4:5], off offset:3072
	global_load_ushort v180, v[4:5], off offset:3584
	v_mad_u64_u32 v[4:5], s[0:1], v2, s85, v[64:65]
	v_or_b32_e32 v2, 4, v7
	v_mad_i32_i24 v5, v3, s85, v5
	v_sub_u32_e32 v3, 0x3ff, v2
	v_cndmask_b32_e32 v2, v3, v2, vcc
	v_ashrrev_i32_e32 v3, 31, v2
	v_lshl_add_u64 v[2:3], s[76:77], 0, v[2:3]
	global_load_ushort v116, v[4:5], off offset:3072
	global_load_ushort v181, v[4:5], off offset:3584
	v_mad_u64_u32 v[4:5], s[0:1], v2, s85, v[64:65]
	v_or_b32_e32 v2, 5, v7
	v_mad_i32_i24 v5, v3, s85, v5
	v_sub_u32_e32 v3, 0x3ff, v2
	v_cndmask_b32_e32 v2, v3, v2, vcc
	v_ashrrev_i32_e32 v3, 31, v2
	v_lshl_add_u64 v[2:3], s[76:77], 0, v[2:3]
	global_load_ushort v119, v[4:5], off offset:3072
	global_load_ushort v182, v[4:5], off offset:3584
	v_mad_u64_u32 v[4:5], s[0:1], v2, s85, v[64:65]
	v_or_b32_e32 v2, 6, v7
	v_mad_i32_i24 v5, v3, s85, v5
	v_sub_u32_e32 v3, 0x3ff, v2
	v_cndmask_b32_e32 v2, v3, v2, vcc
	v_ashrrev_i32_e32 v3, 31, v2
	v_lshl_add_u64 v[2:3], s[76:77], 0, v[2:3]
	global_load_ushort v121, v[4:5], off offset:3072
	global_load_ushort v183, v[4:5], off offset:3584
	v_mad_u64_u32 v[4:5], s[0:1], v2, s85, v[64:65]
	v_or_b32_e32 v2, 7, v7
	v_mad_i32_i24 v5, v3, s85, v5
	v_sub_u32_e32 v3, 0x3ff, v2
	v_cndmask_b32_e32 v2, v3, v2, vcc
	v_ashrrev_i32_e32 v3, 31, v2
	v_lshl_add_u64 v[2:3], s[76:77], 0, v[2:3]
	global_load_ushort v127, v[4:5], off offset:3072
	global_load_ushort v184, v[4:5], off offset:3584
	v_mad_u64_u32 v[4:5], s[0:1], v2, s85, v[64:65]
	v_or_b32_e32 v2, 8, v7
	v_mad_i32_i24 v5, v3, s85, v5
	v_sub_u32_e32 v3, 0x3ff, v2
	v_cndmask_b32_e32 v2, v3, v2, vcc
	v_ashrrev_i32_e32 v3, 31, v2
	v_lshl_add_u64 v[2:3], s[76:77], 0, v[2:3]
	global_load_ushort v137, v[4:5], off offset:3072
	global_load_ushort v185, v[4:5], off offset:3584
	v_mad_u64_u32 v[4:5], s[0:1], v2, s85, v[64:65]
	v_or_b32_e32 v2, 9, v7
	v_mad_i32_i24 v5, v3, s85, v5
	v_sub_u32_e32 v3, 0x3ff, v2
	v_cndmask_b32_e32 v2, v3, v2, vcc
	v_ashrrev_i32_e32 v3, 31, v2
	v_lshl_add_u64 v[2:3], s[76:77], 0, v[2:3]
	global_load_ushort v142, v[4:5], off offset:3072
	global_load_ushort v186, v[4:5], off offset:3584
	v_mad_u64_u32 v[4:5], s[0:1], v2, s85, v[64:65]
	v_or_b32_e32 v2, 10, v7
	v_mad_i32_i24 v5, v3, s85, v5
	v_sub_u32_e32 v3, 0x3ff, v2
	v_cndmask_b32_e32 v2, v3, v2, vcc
	v_ashrrev_i32_e32 v3, 31, v2
	v_lshl_add_u64 v[2:3], s[76:77], 0, v[2:3]
	global_load_ushort v143, v[4:5], off offset:3072
	global_load_ushort v187, v[4:5], off offset:3584
	v_mad_u64_u32 v[4:5], s[0:1], v2, s85, v[64:65]
	v_or_b32_e32 v2, 11, v7
	v_mad_i32_i24 v5, v3, s85, v5
	v_sub_u32_e32 v3, 0x3ff, v2
	v_cndmask_b32_e32 v2, v3, v2, vcc
	v_ashrrev_i32_e32 v3, 31, v2
	v_lshl_add_u64 v[2:3], s[76:77], 0, v[2:3]
	global_load_ushort v197, v[4:5], off offset:3072
	global_load_ushort v188, v[4:5], off offset:3584
	v_mad_u64_u32 v[4:5], s[0:1], v2, s85, v[64:65]
	v_or_b32_e32 v2, 12, v7
	v_mad_i32_i24 v5, v3, s85, v5
	v_sub_u32_e32 v3, 0x3ff, v2
	v_cndmask_b32_e32 v2, v3, v2, vcc
	v_ashrrev_i32_e32 v3, 31, v2
	v_lshl_add_u64 v[2:3], s[76:77], 0, v[2:3]
	global_load_ushort v205, v[4:5], off offset:3072
	global_load_ushort v189, v[4:5], off offset:3584
	v_mad_u64_u32 v[4:5], s[0:1], v2, s85, v[64:65]
	v_or_b32_e32 v2, 13, v7
	v_mad_i32_i24 v5, v3, s85, v5
	v_sub_u32_e32 v3, 0x3ff, v2
	v_cndmask_b32_e32 v2, v3, v2, vcc
	v_ashrrev_i32_e32 v3, 31, v2
	v_lshl_add_u64 v[2:3], s[76:77], 0, v[2:3]
	global_load_ushort v206, v[4:5], off offset:3072
	global_load_ushort v252, v[4:5], off offset:3584
	v_mad_u64_u32 v[4:5], s[0:1], v2, s85, v[64:65]
	v_or_b32_e32 v2, 14, v7
	v_mad_i32_i24 v5, v3, s85, v5
	v_sub_u32_e32 v3, 0x3ff, v2
	v_cndmask_b32_e32 v2, v3, v2, vcc
	v_ashrrev_i32_e32 v3, 31, v2
	v_lshl_add_u64 v[2:3], s[76:77], 0, v[2:3]
	global_load_ushort v207, v[4:5], off offset:3072
	global_load_ushort v253, v[4:5], off offset:3584
	v_mad_u64_u32 v[4:5], s[0:1], v2, s85, v[64:65]
	v_or_b32_e32 v2, 15, v7
	v_mad_i32_i24 v5, v3, s85, v5
	v_sub_u32_e32 v3, 0x3ff, v2
	v_cndmask_b32_e32 v2, v3, v2, vcc
	v_ashrrev_i32_e32 v3, 31, v2
	v_or_b32_e32 v6, s4, v122
	v_sub_u32_e32 v8, v140, v7
	v_lshl_add_u64 v[2:3], s[76:77], 0, v[2:3]
	global_load_ushort v219, v[4:5], off offset:3072
	global_load_ushort v254, v[4:5], off offset:3584
	v_mad_u64_u32 v[4:5], s[0:1], v2, s85, v[64:65]
	v_cndmask_b32_e32 v2, v8, v6, vcc
	v_mad_i32_i24 v5, v3, s85, v5
	v_ashrrev_i32_e32 v3, 31, v2
	v_lshl_add_u64 v[2:3], s[76:77], 0, v[2:3]
	v_mad_u64_u32 v[0:1], s[0:1], v2, s85, v[0:1]
	v_mad_i32_i24 v1, v3, s85, v1
	v_lshl_add_u64 v[0:1], v[66:67], 1, v[0:1]
	v_lshl_add_u64 v[0:1], v[0:1], 0, v[176:177]
	v_add_co_u32_e64 v0, s[56:57], s83, v0
	v_mov_b32_e32 v77, v177
	s_nop 0
	v_addc_co_u32_e64 v1, s[56:57], 0, v1, s[56:57]
	v_mov_b32_e32 v73, v177
	v_mov_b32_e32 v75, v177
	v_lshl_add_u64 v[8:9], v[12:13], 0, v[76:77]
	v_mov_b32_e32 v79, v177
	global_load_ushort v220, v[4:5], off offset:3072
	global_load_ushort v255, v[4:5], off offset:3584
	global_load_dwordx2 v[80:81], v[0:1], off offset:2048
	v_lshl_add_u64 v[4:5], v[12:13], 0, v[74:75]
	global_load_dwordx4 v[8:11], v[8:9], off
	v_lshl_add_u64 v[0:1], v[12:13], 0, v[72:73]
	v_lshl_add_u64 v[12:13], v[12:13], 0, v[78:79]
	global_load_dwordx4 v[0:3], v[0:1], off
	global_load_dwordx4 v[4:7], v[4:5], off
	global_load_dwordx4 v[12:15], v[12:13], off
	s_branch .LBB0_414

; #define LAS __attribute__((address_space(3)))
; DI unsigned pk2(float lo, float hi) { f32x2 v = {lo, hi}; bf16v2 b = __builtin_convertvector(v, bf16v2); return __builtin_bit_cast(unsigned, b); }
; #define BAR_LDS() do { asm volatile("s_waitcnt lgkmcnt(0)" ::: "memory"); __builtin_amdgcn_s_barrier(); asm volatile("" ::: "memory"); } while (0)
; DI void gla_pass2(LAS unsigned char* lds, const Args& A, const bf16* proj, const bf16* scratch, const bf16* QS, const bf16* HT, const float* DD, bf16* glao, int T, int b, int h, int k, int tid_in) {
;     ...
;         for (int j = 0; j < 4; ++j) *(LAS u32x4*)(lds + G2_S0 + dir * 18432 + (vq + 32 * j) * GL_P + oct * 16) =
;             (u32x4){pk2(acc[j][0], acc[j][1]), pk2(acc[j][2], acc[j][3]), pk2(acc[j][4], acc[j][5]), pk2(acc[j][6], acc[j][7])};
;     }
;     BAR_LDS();
;     bf16x8 Bf[2][2];
; #pragma unroll
;     for (int dir = 0; dir < 2; ++dir)
; #pragma unroll
;         for (int ks = 0; ks < 2; ++ks) Bf[dir][ks] = *(const LAS bf16x8*)(lds + G2_S0 + dir * 18432 + (16 * wave + l15) * GL_P + (ks * 32 + 8 * g) * 2);
;     LAS float* OT = (LAS float*)(lds + G2_OT);
;     f32x4 gn[4];
; #pragma unroll
;     for (int j = 0; j < 4; ++j) gn[j] = *(const f32x4*)(A.gla_norm_g + nvc * 16 + 4 * j);
.LBB0_574:
	s_or_b64 exec, exec, s[0:1]
	s_movk_i32 s0, 0x4800
	v_mad_i32_i24 v104, v206, s0, 0
	v_mul_u32_u24_e32 v105, 0x90, v141
	v_add3_u32 v104, v104, v176, v105
	ds_write_b128 v104, v[88:91]
	ds_write_b128 v104, v[92:95] offset:4608
	ds_write_b128 v104, v[96:99] offset:9216
	ds_write_b128 v104, v[100:103] offset:13824
	s_waitcnt lgkmcnt(0)
	s_barrier
	v_lshlrev_b32_e32 v120, 2, v176
	global_load_dwordx4 v[88:91], v120, s[24:25] offset:48
	global_load_dwordx4 v[92:95], v120, s[24:25] offset:32
	global_load_dwordx4 v[96:99], v120, s[24:25] offset:16
	global_load_dwordx4 v[100:103], v120, s[24:25]
	v_and_b32_e32 v121, 0xffffffc0, v204
	v_lshlrev_b32_e32 v122, 2, v136
	v_add3_u32 v124, 0, v121, v122
	v_lshlrev_b32_e32 v122, 5, v204
	v_mov_b32_e32 v137, v177
	v_lshrrev_b32_e32 v104, 2, v204
	s_mov_b32 s0, 0xffffff0
	v_add_u32_e32 v125, 0, v120
	v_lshl_add_u64 v[120:121], v[142:143], 0, s[12:13]
	v_and_b32_e32 v176, 0xe0, v122
	v_and_or_b32 v104, v104, s0, v136
	s_movk_i32 s0, 0x210
	v_lshl_add_u64 v[144:145], v[120:121], 0, v[176:177]
	v_lshl_add_u64 v[120:121], s[42:43], 0, v[136:137]
	v_mul_lo_u32 v126, v138, s0
	s_lshl_b64 s[0:1], s[16:17], 20
	v_lshlrev_b64 v[120:121], 10, v[120:121]
	v_lshl_add_u64 v[120:121], s[0:1], 0, v[120:121]
	v_mul_lo_u32 v104, v104, s86
	v_or_b32_e32 v120, s10, v120
	v_and_b32_e32 v122, 48, v204
	v_mov_b32_e32 v123, v177
	v_add3_u32 v116, 0, v104, v140
	v_lshl_add_u64 v[146:147], v[120:121], 0, v[122:123]
	v_lshl_add_u64 v[120:121], s[42:43], 0, v[138:139]
	ds_read_b128 v[104:107], v116
	ds_read_b128 v[108:111], v116 offset:64
	ds_read_b128 v[112:115], v116 offset:18432
	ds_read_b128 v[116:119], v116 offset:18496
	s_lshl_b64 s[0:1], s[16:17], 21
	v_lshlrev_b64 v[122:123], 11, v[120:121]
	v_lshl_add_u64 v[122:123], s[0:1], 0, v[122:123]
	s_mul_i32 s1, s16, 0xa80000
	v_or3_b32 v122, v122, s12, v176
	s_mul_hi_i32 s0, s16, 0xa80000
	s_or_b32 s1, s1, s12
	v_lshl_add_u64 v[148:149], s[14:15], 0, v[122:123]
	v_mov_b32_e32 v122, s1
	v_mov_b32_e32 v123, s0
	v_mul_u32_u24_e32 v127, 0x840, v205
	v_mad_u64_u32 v[122:123], s[0:1], v120, s85, v[122:123]
	v_mad_i32_i24 v151, v121, s85, v123
	v_or_b32_e32 v150, v122, v176
	v_add_u32_e32 v152, v124, v127
	v_add_u32_e32 v153, v125, v126
	s_waitcnt vmcnt(9)
	v_mov_b64_e32 v[122:123], v[70:71]
	s_waitcnt vmcnt(8)
	v_mov_b64_e32 v[126:127], v[66:67]
	s_waitcnt vmcnt(6)
	v_mov_b64_e32 v[130:131], v[86:87]
	v_mov_b64_e32 v[134:135], v[78:79]
	s_waitcnt vmcnt(4)
	v_mov_b64_e32 v[138:139], v[82:83]
	v_mov_b64_e32 v[142:143], v[74:75]
	s_mov_b64 s[16:17], 0
	v_mov_b64_e32 v[120:121], v[68:69]
	v_mov_b64_e32 v[124:125], v[64:65]
	v_mov_b64_e32 v[128:129], v[84:85]
	v_mov_b64_e32 v[132:133], v[76:77]
	v_mov_b64_e32 v[136:137], v[80:81]
	v_mov_b64_e32 v[140:141], v[72:73]
	s_waitcnt vmcnt(0)
	s_branch .LBB0_576
.LBB0_575:
	s_waitcnt lgkmcnt(0)
	s_barrier
	s_nop 2
	v_lshlrev_b32_e32 v154, 16, v84
	v_and_b32_e32 v155, 0xffff0000, v84
	v_lshlrev_b32_e32 v156, 16, v80
	v_and_b32_e32 v157, 0xffff0000, v80
	v_pk_add_f32 v[170:171], v[156:157], v[154:155]
	ds_read_b128 v[154:157], v153 offset:36864
	v_lshlrev_b32_e32 v84, 16, v85
	v_and_b32_e32 v85, 0xffff0000, v85
	v_lshlrev_b32_e32 v80, 16, v81
	v_and_b32_e32 v81, 0xffff0000, v81
	v_pk_add_f32 v[80:81], v[80:81], v[84:85]
	s_waitcnt lgkmcnt(0)
	v_pk_add_f32 v[84:85], v[170:171], v[154:155]
	v_pk_add_f32 v[80:81], v[80:81], v[156:157]
	v_pk_mul_f32 v[156:157], v[84:85], v[84:85]
	v_pk_mul_f32 v[154:155], v[80:81], v[80:81]
	ds_read_b128 v[158:161], v153 offset:36880
	ds_read_b128 v[162:165], v153 offset:36896
	ds_read_b128 v[166:169], v153 offset:36912
	v_pk_mov_b32 v[170:171], v[156:157], v[154:155] op_sel:[1,0]
	v_mov_b32_e32 v157, v155
	v_pk_add_f32 v[154:155], v[170:171], v[156:157]
	v_lshlrev_b32_e32 v156, 16, v86
	v_and_b32_e32 v157, 0xffff0000, v86
	v_lshlrev_b32_e32 v170, 16, v82
	v_and_b32_e32 v171, 0xffff0000, v82
	v_lshlrev_b32_e32 v86, 16, v87
	v_and_b32_e32 v87, 0xffff0000, v87
	v_lshlrev_b32_e32 v82, 16, v83
	v_and_b32_e32 v83, 0xffff0000, v83
	v_pk_add_f32 v[156:157], v[170:171], v[156:157]
	v_pk_add_f32 v[82:83], v[82:83], v[86:87]
	s_waitcnt lgkmcnt(2)
	v_pk_add_f32 v[86:87], v[156:157], v[158:159]
	v_pk_add_f32 v[82:83], v[82:83], v[160:161]
	v_pk_mul_f32 v[158:159], v[86:87], v[86:87]
	v_pk_mul_f32 v[156:157], v[82:83], v[82:83]
	v_pk_add_f32 v[154:155], v[154:155], v[154:155] op_sel:[0,1] op_sel_hi:[1,0]
	v_pk_mov_b32 v[160:161], v[158:159], v[156:157] op_sel:[1,0]
	v_mov_b32_e32 v159, v157
	v_pk_add_f32 v[156:157], v[160:161], v[158:159]
	v_lshlrev_b32_e32 v158, 16, v76
	v_and_b32_e32 v159, 0xffff0000, v76
	v_lshlrev_b32_e32 v160, 16, v72
	v_and_b32_e32 v161, 0xffff0000, v72
	v_pk_add_f32 v[158:159], v[160:161], v[158:159]
	v_lshlrev_b32_e32 v76, 16, v77
	v_and_b32_e32 v77, 0xffff0000, v77
	v_lshlrev_b32_e32 v72, 16, v73
	v_and_b32_e32 v73, 0xffff0000, v73
	v_pk_add_f32 v[72:73], v[72:73], v[76:77]
	s_waitcnt lgkmcnt(1)
; #define LAS __attribute__((address_space(3)))
; DI unsigned pk2(float lo, float hi) { f32x2 v = {lo, hi}; bf16v2 b = __builtin_convertvector(v, bf16v2); return __builtin_bit_cast(unsigned, b); }
; DI void gla_pass2(LAS unsigned char* lds, const Args& A, const bf16* proj, const bf16* scratch, const bf16* QS, const bf16* HT, const float* DD, bf16* glao, int T, int b, int h, int k, int tid_in) {
;     ...
;         const u32x4 gw0 = gw[0], gw1 = gw[1], sf0 = SC[0][0], sf1 = SC[0][1], sb0 = SC[1][0], sb1 = SC[1][1];
;         if (grp + 1 < GSEG / 64) G2_LOAD(grp + 1);
;         BAR_LDS();
;         {   const size_t row = rowb + grp * 64 + ntk; f32x4 sv[4]; float ss = 0.f;
; #pragma unroll
;             for (int j = 0; j < 4; ++j) { const u32x4 cf = (j < 2) ? sf0 : sf1, cb = (j < 2) ? sb0 : sb1; const unsigned f0 = cf[2 * (j & 1)], f1 = cf[2 * (j & 1) + 1], b0 = cb[2 * (j & 1)], b1 = cb[2 * (j & 1) + 1];
;                 f32x4 lo; lo.x = __uint_as_float(f0 << 16) + __uint_as_float(b0 << 16); lo.y = __uint_as_float(f0 & 0xffff0000u) + __uint_as_float(b0 & 0xffff0000u);
;                 lo.z = __uint_as_float(f1 << 16) + __uint_as_float(b1 << 16); lo.w = __uint_as_float(f1 & 0xffff0000u) + __uint_as_float(b1 & 0xffff0000u);
;                 sv[j] = *(const LAS f32x4*)(OT + ntk * G2_OTP + nvc * 16 + 4 * j) + lo; ss += (sv[j].x * sv[j].x + sv[j].y * sv[j].y) + (sv[j].z * sv[j].z + sv[j].w * sv[j].w); }
;             ss += __shfl_xor(ss, 1); ss += __shfl_xor(ss, 2); ss += __shfl_xor(ss, 4);
;             const float rstd = rsqrtf(ss * (1.0f / 128.0f) + RMS_EPS);
;             u32x4* op = (u32x4*)(glao + row * DM + h * 128 + nvc * 16);
; #pragma unroll
;             for (int j2 = 0; j2 < 2; ++j2) { const u32x4 gq = j2 ? gw1 : gw0; const f32x4 a = sv[2 * j2] * rstd * gn[2 * j2], bb = sv[2 * j2 + 1] * rstd * gn[2 * j2 + 1];
;                 u32x4 w;
;                 w.x = pk2(a.x * __uint_as_float(gq.x << 16), a.y * __uint_as_float(gq.x & 0xffff0000u)); w.y = pk2(a.z * __uint_as_float(gq.y << 16), a.w * __uint_as_float(gq.y & 0xffff0000u));
;                 w.z = pk2(bb.x * __uint_as_float(gq.z << 16), bb.y * __uint_as_float(gq.z & 0xffff0000u)); w.w = pk2(bb.z * __uint_as_float(gq.w << 16), bb.w * __uint_as_float(gq.w & 0xffff0000u));
;                 op[j2] = w; }
;         }
;         BAR_LDS();
	v_pk_add_f32 v[76:77], v[158:159], v[162:163]
	v_lshlrev_b32_e32 v158, 16, v78
	v_and_b32_e32 v159, 0xffff0000, v78
	v_lshlrev_b32_e32 v160, 16, v74
	v_and_b32_e32 v161, 0xffff0000, v74
	v_pk_add_f32 v[158:159], v[160:161], v[158:159]
	v_lshlrev_b32_e32 v78, 16, v79
	v_and_b32_e32 v79, 0xffff0000, v79
	v_lshlrev_b32_e32 v74, 16, v75
	v_and_b32_e32 v75, 0xffff0000, v75
	v_pk_add_f32 v[74:75], v[74:75], v[78:79]
	s_waitcnt lgkmcnt(0)
	v_pk_add_f32 v[78:79], v[158:159], v[166:167]
	v_pk_add_f32 v[156:157], v[156:157], v[156:157] op_sel:[0,1] op_sel_hi:[1,0]
	v_mul_f32_e32 v158, v78, v78
	v_mul_f32_e32 v159, v79, v79
	v_pk_add_f32 v[72:73], v[72:73], v[164:165]
	v_mov_b32_e32 v155, v158
	v_mov_b32_e32 v157, v159
	v_pk_add_f32 v[74:75], v[74:75], v[168:169]
	v_pk_add_f32 v[154:155], v[154:155], v[156:157]
	v_mul_f32_e32 v156, v77, v77
	v_mul_f32_e32 v158, v73, v73
	v_mul_f32_e32 v160, v74, v74
	v_mul_f32_e32 v161, v75, v75
	v_pk_fma_f32 v[156:157], v[76:77], v[76:77], v[156:157] op_sel_hi:[1,1,0]
	v_pk_fma_f32 v[158:159], v[72:73], v[72:73], v[158:159] op_sel_hi:[1,1,0]
	v_mov_b32_e32 v157, v160
	v_mov_b32_e32 v159, v161
	v_pk_add_f32 v[156:157], v[156:157], v[158:159]
	v_lshlrev_b32_e32 v158, 16, v68
	v_pk_add_f32 v[154:155], v[154:155], v[156:157]
	v_and_b32_e32 v156, 64, v211
	v_add_f32_e32 v154, v154, v155
	v_xor_b32_e32 v155, 1, v211
	v_add_u32_e32 v156, 64, v156
	v_cmp_lt_i32_e32 vcc, v155, v156
	v_and_b32_e32 v159, 0xffff0000, v68
	s_mov_b32 s0, 0xa200000
	v_cndmask_b32_e32 v155, v211, v155, vcc
	v_lshlrev_b32_e32 v155, 2, v155
	ds_bpermute_b32 v155, v155, v154
	s_add_u32 s16, s16, 0x20000
	s_addc_u32 s17, s17, 0
	s_cmp_lg_u32 s16, 0x200000
	s_waitcnt lgkmcnt(0)
	v_add_f32_e32 v154, v154, v155
	v_xor_b32_e32 v155, 2, v211
	v_cmp_lt_i32_e32 vcc, v155, v156
	s_nop 1
	v_cndmask_b32_e32 v155, v211, v155, vcc
	v_lshlrev_b32_e32 v155, 2, v155
	ds_bpermute_b32 v155, v155, v154
	s_waitcnt lgkmcnt(0)
	v_add_f32_e32 v154, v154, v155
	v_xor_b32_e32 v155, 4, v211
	v_cmp_lt_i32_e32 vcc, v155, v156
	v_lshl_add_u64 v[156:157], s[60:61], 0, v[144:145]
	v_lshl_add_u64 v[144:145], v[144:145], 0, s[58:59]
	v_cndmask_b32_e32 v155, v211, v155, vcc
	v_lshlrev_b32_e32 v155, 2, v155
	ds_bpermute_b32 v155, v155, v154
	s_waitcnt lgkmcnt(0)
	v_add_f32_e32 v154, v154, v155
	v_fmamk_f32 v154, v154, 0x3c000000, v210
	v_mul_f32_e32 v155, 0x4b800000, v154
	v_cmp_gt_f32_e32 vcc, s91, v154
	s_nop 1
	v_cndmask_b32_e32 v154, v154, v155, vcc
	v_rsq_f32_e32 v154, v154
	s_nop 0
	v_mul_f32_e32 v155, 0x45800000, v154
	v_cndmask_b32_e32 v154, v154, v155, vcc
	v_pk_mul_f32 v[84:85], v[84:85], v[154:155] op_sel_hi:[1,0]
	v_pk_mul_f32 v[80:81], v[80:81], v[154:155] op_sel_hi:[1,0]
	s_nop 0
	v_pk_mul_f32 v[84:85], v[100:101], v[84:85]
	v_pk_mul_f32 v[80:81], v[102:103], v[80:81]
	v_pk_mul_f32 v[84:85], v[84:85], v[158:159]
	v_pk_mul_f32 v[86:87], v[86:87], v[154:155] op_sel_hi:[1,0]
	v_cvt_pk_bf16_f32 v68, v84, v85
	v_lshlrev_b32_e32 v84, 16, v69
	v_and_b32_e32 v85, 0xffff0000, v69
	v_pk_mul_f32 v[80:81], v[80:81], v[84:85]
	v_pk_mul_f32 v[86:87], v[96:97], v[86:87]
	v_cvt_pk_bf16_f32 v69, v80, v81
	v_lshlrev_b32_e32 v80, 16, v70
	v_and_b32_e32 v81, 0xffff0000, v70
	v_pk_mul_f32 v[82:83], v[82:83], v[154:155] op_sel_hi:[1,0]
	v_pk_mul_f32 v[80:81], v[86:87], v[80:81]
	v_pk_mul_f32 v[82:83], v[98:99], v[82:83]
	v_cvt_pk_bf16_f32 v70, v80, v81
	v_lshlrev_b32_e32 v80, 16, v71
	v_and_b32_e32 v81, 0xffff0000, v71
	v_pk_mul_f32 v[80:81], v[82:83], v[80:81]
	v_pk_mul_f32 v[74:75], v[74:75], v[154:155] op_sel_hi:[1,0]
	v_cvt_pk_bf16_f32 v71, v80, v81
	v_add_co_u32_e32 v80, vcc, s0, v156
	v_pk_mul_f32 v[74:75], v[90:91], v[74:75]
	s_nop 0
	v_addc_co_u32_e32 v81, vcc, 0, v157, vcc
	global_store_dwordx4 v[80:81], v[68:71], off offset:1024
	s_mov_b64 s[0:1], 0x10000
	v_lshl_add_u64 v[146:147], v[146:147], 0, s[0:1]
	v_pk_mul_f32 v[68:69], v[76:77], v[154:155] op_sel_hi:[1,0]
	v_lshlrev_b32_e32 v76, 16, v64
	v_pk_mul_f32 v[68:69], v[92:93], v[68:69]
	v_and_b32_e32 v77, 0xffff0000, v64
	v_pk_mul_f32 v[70:71], v[72:73], v[154:155] op_sel_hi:[1,0]
	v_pk_mul_f32 v[68:69], v[68:69], v[76:77]
	v_pk_mul_f32 v[70:71], v[94:95], v[70:71]
	v_cvt_pk_bf16_f32 v64, v68, v69
	v_lshlrev_b32_e32 v68, 16, v65
	v_and_b32_e32 v69, 0xffff0000, v65
	v_pk_mul_f32 v[72:73], v[78:79], v[154:155] op_sel_hi:[1,0]
	v_pk_mul_f32 v[68:69], v[70:71], v[68:69]
	v_pk_mul_f32 v[72:73], v[88:89], v[72:73]
	v_cvt_pk_bf16_f32 v65, v68, v69
	v_lshlrev_b32_e32 v68, 16, v66
	v_and_b32_e32 v69, 0xffff0000, v66
	v_pk_mul_f32 v[68:69], v[72:73], v[68:69]
	s_mov_b64 s[0:1], 0xa8000
	v_cvt_pk_bf16_f32 v66, v68, v69
	v_lshlrev_b32_e32 v68, 16, v67
	v_and_b32_e32 v69, 0xffff0000, v67
	v_pk_mul_f32 v[68:69], v[74:75], v[68:69]
	s_waitcnt vmcnt(1)
	v_mov_b64_e32 v[72:73], v[140:141]
	v_cvt_pk_bf16_f32 v67, v68, v69
	global_store_dwordx4 v[80:81], v[64:67], off offset:1040
	s_waitcnt lgkmcnt(0)
	s_barrier
	v_mov_b64_e32 v[80:81], v[136:137]
	v_mov_b64_e32 v[76:77], v[132:133]
	v_mov_b64_e32 v[84:85], v[128:129]
	v_mov_b64_e32 v[64:65], v[124:125]
	v_mov_b64_e32 v[68:69], v[120:121]
	v_lshl_add_u64 v[150:151], v[150:151], 0, s[0:1]
	v_mov_b64_e32 v[74:75], v[142:143]
	v_mov_b64_e32 v[82:83], v[138:139]
	v_mov_b64_e32 v[78:79], v[134:135]
	v_mov_b64_e32 v[86:87], v[130:131]
	v_mov_b64_e32 v[66:67], v[126:127]
	v_mov_b64_e32 v[70:71], v[122:123]
	s_cbranch_scc0 .LBB0_567

; __device__ __forceinline__ unsigned cvt_pk_bf16(float lo, float hi) { unsigned r; asm volatile("v_cvt_pk_bf16_f32 %0, %1, %2" : "=v"(r) : "v"(lo), "v"(hi)); return r; }
;     __device__ __forceinline__ void operator()(const f32x4 (&acc)[2][2][4][2], const Unit& u, int wr, int wc, int fr, int fq) const {
;         const int row0 = u.pm * BM + wr * 64 + fr, col0 = u.pn * BM + wc * 32 + 8 * fq;
; #pragma unroll
;         for (int ai = 0; ai < 2; ++ai)
; #pragma unroll
;             for (int m = 0; m < 4; ++m) { const size_t r = (size_t)(row0 + ai * HALF + m * 16);
;                 const float rstd = rsqrtf(ssq[r] * (1.0f / DM) + RMS_EPS);
; #pragma unroll
;                 for (int bj = 0; bj < 2; ++bj) { f32x4 v0 = acc[ai][bj][m][0] * rstd, v1 = acc[ai][bj][m][1] * rstd;
; #pragma unroll
;                     for (int e = 0; e < 4; ++e) { const float a = fmaxf(v0[e], 0.f), b = fmaxf(v1[e], 0.f); v0[e] = a * a; v1[e] = b * b; }
;                     u32x4 w; w.x = cvt_pk_bf16(v0[0], v0[1]); w.y = cvt_pk_bf16(v0[2], v0[3]); w.z = cvt_pk_bf16(v1[0], v1[1]); w.w = cvt_pk_bf16(v1[2], v1[3]);
;                     const int col = col0 + bj * HALF;
;                     *(u32x4*)(O + ((((r >> 8) * (DFF / 64) + (col >> 6)) * 256 + (r & 255)) * 64 + (col & 63))) = w; } }
.LBB0_811:
	v_lshl_add_u32 v142, s5, 8, v148
	v_ashrrev_i32_e32 v143, 31, v142
	v_lshl_add_u64 v[144:145], v[142:143], 2, s[48:49]
	global_load_dword v141, v[144:145], off
	global_load_dword v220, v[144:145], off offset:64
	global_load_dword v221, v[144:145], off offset:128
	global_load_dword v222, v[144:145], off offset:192
	global_load_dword v223, v[144:145], off offset:512
	global_load_dword v224, v[144:145], off offset:576
	global_load_dword v225, v[144:145], off offset:640
	global_load_dword v226, v[144:145], off offset:704
	s_lshl_b32 s0, s4, 8
	s_or_b32 s0, s0, s76
	s_ashr_i32 s64, s0, 6
	s_ashr_i32 s65, s64, 31
	s_or_b32 s66, s64, 2
	s_ashr_i32 s67, s66, 31
	s_mov_b64 s[18:19], -1
	s_waitcnt vmcnt(0)
	v_fmamk_f32 v141, v141, 0x3a800000, v210
	v_cmp_gt_f32_e32 vcc, s91, v141
	v_mul_f32_e32 v146, 0x4b800000, v141
	s_nop 0
	v_cndmask_b32_e32 v141, v141, v146, vcc
	v_rsq_f32_e32 v141, v141
	s_nop 0
	v_mul_f32_e32 v146, 0x45800000, v141
	v_cndmask_b32_e32 v152, v141, v146, vcc
	v_pk_mul_f32 v[126:127], v[126:127], v[152:153] op_sel_hi:[1,0]
	v_pk_mul_f32 v[124:125], v[124:125], v[152:153] op_sel_hi:[1,0]
	v_pk_mul_f32 v[120:121], v[120:121], v[152:153] op_sel_hi:[1,0]
	v_lshrrev_b64 v[146:147], 2, v[142:143]
	v_pk_mul_f32 v[122:123], v[122:123], v[152:153] op_sel_hi:[1,0]
	v_max_f32_e32 v124, 0, v124
	v_max_f32_e32 v120, 0, v120
	v_max_f32_e32 v125, 0, v125
	v_max_f32_e32 v121, 0, v121
	v_max_f32_e32 v126, 0, v126
	v_and_b32_e32 v147, 0x1ffff, v147
	v_and_b32_e32 v146, 0xffffffc0, v146
	v_mul_f32_e32 v124, v124, v124
	v_mul_f32_e32 v120, v120, v120
	v_mul_f32_e32 v125, v125, v125
	v_mul_f32_e32 v121, v121, v121
	v_max_f32_e32 v122, 0, v122
	v_mul_f32_e32 v126, v126, v126
	v_max_f32_e32 v127, 0, v127
	v_mul_f32_e32 v122, v122, v122
	v_max_f32_e32 v123, 0, v123
	v_mul_f32_e32 v127, v127, v127
	v_cvt_pk_bf16_f32 v124, v124, v125
	v_cvt_pk_bf16_f32 v125, v126, v127
	v_cvt_pk_bf16_f32 v126, v120, v121
	v_lshl_add_u64 v[120:121], v[146:147], 0, s[64:65]
	v_mul_f32_e32 v123, v123, v123
	v_cvt_pk_bf16_f32 v127, v122, v123
	v_lshlrev_b64 v[120:121], 15, v[120:121]
	v_lshlrev_b32_e32 v122, 7, v142
	v_pk_mul_f32 v[114:115], v[114:115], v[152:153] op_sel_hi:[1,0]
	v_pk_mul_f32 v[112:113], v[112:113], v[152:153] op_sel_hi:[1,0]
	v_lshl_add_u64 v[120:121], s[70:71], 0, v[120:121]
	v_and_b32_e32 v176, 0x6780, v122
	v_pk_mul_f32 v[118:119], v[118:119], v[152:153] op_sel_hi:[1,0]
	v_pk_mul_f32 v[116:117], v[116:117], v[152:153] op_sel_hi:[1,0]
	v_max_f32_e32 v112, 0, v112
	v_max_f32_e32 v113, 0, v113
	v_max_f32_e32 v114, 0, v114
	v_lshl_add_u64 v[154:155], v[120:121], 0, v[176:177]
	v_mov_b32_e32 v141, v177
	v_max_f32_e32 v116, 0, v116
	v_mul_f32_e32 v123, v112, v112
	v_max_f32_e32 v112, 0, v117
	v_mul_f32_e32 v117, v113, v113
	v_max_f32_e32 v113, 0, v118
	v_mul_f32_e32 v118, v114, v114
	v_max_f32_e32 v114, 0, v119
	v_lshl_add_u64 v[154:155], v[154:155], 0, v[140:141]
	v_mul_f32_e32 v116, v116, v116
	v_mul_f32_e32 v112, v112, v112
	v_mul_f32_e32 v113, v113, v113
	v_mul_f32_e32 v114, v114, v114
	global_store_dwordx4 v[154:155], v[124:127], off
	v_cvt_pk_bf16_f32 v112, v116, v112
	v_cvt_pk_bf16_f32 v113, v113, v114
	v_cvt_pk_bf16_f32 v114, v123, v117
	v_lshl_add_u64 v[116:117], v[146:147], 0, s[66:67]
	v_max_f32_e32 v115, 0, v115
	v_lshlrev_b64 v[116:117], 15, v[116:117]
	v_mul_f32_e32 v115, v115, v115
	v_lshl_add_u64 v[116:117], s[70:71], 0, v[116:117]
	v_cvt_pk_bf16_f32 v115, v118, v115
	v_lshl_add_u64 v[118:119], v[116:117], 0, v[176:177]
	v_lshl_add_u64 v[118:119], v[118:119], 0, v[140:141]
	global_store_dwordx4 v[118:119], v[112:115], off
	s_nop 0
	v_bitop3_b32 v176, v122, s92, v216 bitop3:0xc8
	s_nop 1
	v_fmamk_f32 v112, v220, 0x3a800000, v210
	v_cmp_gt_f32_e32 vcc, s91, v112
	v_mul_f32_e32 v113, 0x4b800000, v112
	s_nop 0
	v_cndmask_b32_e32 v112, v112, v113, vcc
	v_rsq_f32_e32 v112, v112
	s_nop 0
	v_mul_f32_e32 v113, 0x45800000, v112
	v_cndmask_b32_e32 v112, v112, v113, vcc
	v_pk_mul_f32 v[106:107], v[106:107], v[112:113] op_sel_hi:[1,0]
	v_pk_mul_f32 v[104:105], v[104:105], v[112:113] op_sel_hi:[1,0]
	v_pk_mul_f32 v[110:111], v[110:111], v[112:113] op_sel_hi:[1,0]
	v_pk_mul_f32 v[108:109], v[108:109], v[112:113] op_sel_hi:[1,0]
	v_max_f32_e32 v104, 0, v104
	v_max_f32_e32 v105, 0, v105
	v_max_f32_e32 v106, 0, v106
	v_max_f32_e32 v108, 0, v108
	v_mul_f32_e32 v113, v104, v104
	v_max_f32_e32 v104, 0, v109
	v_mul_f32_e32 v109, v105, v105
	v_max_f32_e32 v105, 0, v110
	v_mul_f32_e32 v110, v106, v106
	v_max_f32_e32 v106, 0, v111
	v_mul_f32_e32 v108, v108, v108
	v_mul_f32_e32 v104, v104, v104
	v_mul_f32_e32 v105, v105, v105
	v_mul_f32_e32 v106, v106, v106
	v_max_f32_e32 v107, 0, v107
	v_cvt_pk_bf16_f32 v104, v108, v104
	v_cvt_pk_bf16_f32 v105, v105, v106
	v_cvt_pk_bf16_f32 v106, v113, v109
	v_lshl_add_u64 v[108:109], v[120:121], 0, v[176:177]
	v_pk_mul_f32 v[98:99], v[98:99], v[112:113] op_sel_hi:[1,0]
	v_pk_mul_f32 v[96:97], v[96:97], v[112:113] op_sel_hi:[1,0]
	v_mul_f32_e32 v107, v107, v107
	v_lshl_add_u64 v[108:109], v[108:109], 0, v[140:141]
	v_pk_mul_f32 v[102:103], v[102:103], v[112:113] op_sel_hi:[1,0]
	v_pk_mul_f32 v[100:101], v[100:101], v[112:113] op_sel_hi:[1,0]
	v_max_f32_e32 v96, 0, v96
	v_max_f32_e32 v97, 0, v97
	v_max_f32_e32 v98, 0, v98
	v_cvt_pk_bf16_f32 v107, v110, v107
	global_store_dwordx4 v[108:109], v[104:107], off
	v_max_f32_e32 v100, 0, v100
	v_mul_f32_e32 v100, v100, v100
	v_mul_f32_e32 v104, v96, v96
	v_max_f32_e32 v96, 0, v101
	v_mul_f32_e32 v101, v97, v97
	v_max_f32_e32 v97, 0, v102
	v_mul_f32_e32 v102, v98, v98
	v_max_f32_e32 v98, 0, v103
	v_mul_f32_e32 v96, v96, v96
	v_mul_f32_e32 v97, v97, v97
	v_mul_f32_e32 v98, v98, v98
; __device__ __forceinline__ unsigned cvt_pk_bf16(float lo, float hi) { unsigned r; asm volatile("v_cvt_pk_bf16_f32 %0, %1, %2" : "=v"(r) : "v"(lo), "v"(hi)); return r; }
;     __device__ __forceinline__ void operator()(const f32x4 (&acc)[2][2][4][2], const Unit& u, int wr, int wc, int fr, int fq) const {
;         const int row0 = u.pm * BM + wr * 64 + fr, col0 = u.pn * BM + wc * 32 + 8 * fq;
; #pragma unroll
;         for (int ai = 0; ai < 2; ++ai)
; #pragma unroll
;             for (int m = 0; m < 4; ++m) { const size_t r = (size_t)(row0 + ai * HALF + m * 16);
;                 const float rstd = rsqrtf(ssq[r] * (1.0f / DM) + RMS_EPS);
; #pragma unroll
;                 for (int bj = 0; bj < 2; ++bj) { f32x4 v0 = acc[ai][bj][m][0] * rstd, v1 = acc[ai][bj][m][1] * rstd;
; #pragma unroll
;                     for (int e = 0; e < 4; ++e) { const float a = fmaxf(v0[e], 0.f), b = fmaxf(v1[e], 0.f); v0[e] = a * a; v1[e] = b * b; }
;                     u32x4 w; w.x = cvt_pk_bf16(v0[0], v0[1]); w.y = cvt_pk_bf16(v0[2], v0[3]); w.z = cvt_pk_bf16(v1[0], v1[1]); w.w = cvt_pk_bf16(v1[2], v1[3]);
;                     const int col = col0 + bj * HALF;
;                     *(u32x4*)(O + ((((r >> 8) * (DFF / 64) + (col >> 6)) * 256 + (r & 255)) * 64 + (col & 63))) = w; } }
	v_max_f32_e32 v99, 0, v99
	v_cvt_pk_bf16_f32 v96, v100, v96
	v_cvt_pk_bf16_f32 v97, v97, v98
	v_cvt_pk_bf16_f32 v98, v104, v101
	v_lshl_add_u64 v[100:101], v[116:117], 0, v[176:177]
	v_mul_f32_e32 v99, v99, v99
	v_lshl_add_u64 v[100:101], v[100:101], 0, v[140:141]
	v_cvt_pk_bf16_f32 v99, v102, v99
	global_store_dwordx4 v[100:101], v[96:99], off
	s_nop 0
	v_bitop3_b32 v176, v122, s92, v217 bitop3:0xc8
	s_nop 1
	v_fmamk_f32 v96, v221, 0x3a800000, v210
	v_cmp_gt_f32_e32 vcc, s91, v96
	v_mul_f32_e32 v97, 0x4b800000, v96
	s_nop 0
	v_cndmask_b32_e32 v96, v96, v97, vcc
	v_rsq_f32_e32 v96, v96
	s_nop 0
	v_mul_f32_e32 v97, 0x45800000, v96
	v_cndmask_b32_e32 v96, v96, v97, vcc
	v_pk_mul_f32 v[90:91], v[90:91], v[96:97] op_sel_hi:[1,0]
	v_pk_mul_f32 v[88:89], v[88:89], v[96:97] op_sel_hi:[1,0]
	v_pk_mul_f32 v[94:95], v[94:95], v[96:97] op_sel_hi:[1,0]
	v_pk_mul_f32 v[92:93], v[92:93], v[96:97] op_sel_hi:[1,0]
	v_max_f32_e32 v88, 0, v88
	v_max_f32_e32 v89, 0, v89
	v_max_f32_e32 v90, 0, v90
	v_max_f32_e32 v92, 0, v92
	v_mul_f32_e32 v97, v88, v88
	v_max_f32_e32 v88, 0, v93
	v_mul_f32_e32 v93, v89, v89
	v_max_f32_e32 v89, 0, v94
	v_mul_f32_e32 v94, v90, v90
	v_max_f32_e32 v90, 0, v95
	v_mul_f32_e32 v92, v92, v92
	v_mul_f32_e32 v88, v88, v88
	v_mul_f32_e32 v89, v89, v89
	v_mul_f32_e32 v90, v90, v90
	v_max_f32_e32 v91, 0, v91
	v_cvt_pk_bf16_f32 v88, v92, v88
	v_cvt_pk_bf16_f32 v89, v89, v90
	v_cvt_pk_bf16_f32 v90, v97, v93
	v_lshl_add_u64 v[92:93], v[120:121], 0, v[176:177]
	v_pk_mul_f32 v[82:83], v[82:83], v[96:97] op_sel_hi:[1,0]
	v_pk_mul_f32 v[80:81], v[80:81], v[96:97] op_sel_hi:[1,0]
	v_mul_f32_e32 v91, v91, v91
	v_lshl_add_u64 v[92:93], v[92:93], 0, v[140:141]
	v_pk_mul_f32 v[86:87], v[86:87], v[96:97] op_sel_hi:[1,0]
	v_pk_mul_f32 v[84:85], v[84:85], v[96:97] op_sel_hi:[1,0]
	v_max_f32_e32 v80, 0, v80
	v_max_f32_e32 v81, 0, v81
	v_max_f32_e32 v82, 0, v82
	v_cvt_pk_bf16_f32 v91, v94, v91
	global_store_dwordx4 v[92:93], v[88:91], off
	v_max_f32_e32 v84, 0, v84
	v_mul_f32_e32 v84, v84, v84
	v_mul_f32_e32 v88, v80, v80
	v_max_f32_e32 v80, 0, v85
	v_mul_f32_e32 v85, v81, v81
	v_max_f32_e32 v81, 0, v86
	v_mul_f32_e32 v86, v82, v82
	v_max_f32_e32 v82, 0, v87
	v_mul_f32_e32 v80, v80, v80
	v_mul_f32_e32 v81, v81, v81
	v_mul_f32_e32 v82, v82, v82
	v_max_f32_e32 v83, 0, v83
	v_cvt_pk_bf16_f32 v80, v84, v80
	v_cvt_pk_bf16_f32 v81, v81, v82
	v_cvt_pk_bf16_f32 v82, v88, v85
	v_lshl_add_u64 v[84:85], v[116:117], 0, v[176:177]
	v_mul_f32_e32 v83, v83, v83
	v_lshl_add_u64 v[84:85], v[84:85], 0, v[140:141]
	v_cvt_pk_bf16_f32 v83, v86, v83
	global_store_dwordx4 v[84:85], v[80:83], off
	s_nop 0
	v_bitop3_b32 v176, v122, s92, v218 bitop3:0xc8
	s_nop 1
	v_fmamk_f32 v80, v222, 0x3a800000, v210
	v_cmp_gt_f32_e32 vcc, s91, v80
	v_mul_f32_e32 v81, 0x4b800000, v80
	s_nop 0
	v_cndmask_b32_e32 v80, v80, v81, vcc
	v_rsq_f32_e32 v80, v80
	s_nop 0
	v_mul_f32_e32 v81, 0x45800000, v80
	v_cndmask_b32_e32 v80, v80, v81, vcc
	v_pk_mul_f32 v[74:75], v[74:75], v[80:81] op_sel_hi:[1,0]
	v_pk_mul_f32 v[72:73], v[72:73], v[80:81] op_sel_hi:[1,0]
	v_pk_mul_f32 v[78:79], v[78:79], v[80:81] op_sel_hi:[1,0]
	v_pk_mul_f32 v[76:77], v[76:77], v[80:81] op_sel_hi:[1,0]
	v_max_f32_e32 v72, 0, v72
	v_max_f32_e32 v73, 0, v73
	v_max_f32_e32 v74, 0, v74
	v_max_f32_e32 v76, 0, v76
	v_mul_f32_e32 v81, v72, v72
	v_max_f32_e32 v72, 0, v77
	v_mul_f32_e32 v77, v73, v73
	v_max_f32_e32 v73, 0, v78
	v_mul_f32_e32 v78, v74, v74
	v_max_f32_e32 v74, 0, v79
	v_mul_f32_e32 v76, v76, v76
	v_mul_f32_e32 v72, v72, v72
	v_mul_f32_e32 v73, v73, v73
	v_mul_f32_e32 v74, v74, v74
	v_max_f32_e32 v75, 0, v75
	v_cvt_pk_bf16_f32 v72, v76, v72
	v_cvt_pk_bf16_f32 v73, v73, v74
	v_cvt_pk_bf16_f32 v74, v81, v77
	v_lshl_add_u64 v[76:77], v[120:121], 0, v[176:177]
	v_pk_mul_f32 v[66:67], v[66:67], v[80:81] op_sel_hi:[1,0]
	v_pk_mul_f32 v[64:65], v[64:65], v[80:81] op_sel_hi:[1,0]
	v_mul_f32_e32 v75, v75, v75
	v_lshl_add_u64 v[76:77], v[76:77], 0, v[140:141]
	v_pk_mul_f32 v[70:71], v[70:71], v[80:81] op_sel_hi:[1,0]
	v_pk_mul_f32 v[68:69], v[68:69], v[80:81] op_sel_hi:[1,0]
	v_max_f32_e32 v64, 0, v64
	v_max_f32_e32 v65, 0, v65
	v_max_f32_e32 v66, 0, v66
	v_cvt_pk_bf16_f32 v75, v78, v75
	global_store_dwordx4 v[76:77], v[72:75], off
	v_max_f32_e32 v68, 0, v68
	v_mul_f32_e32 v68, v68, v68
	v_mul_f32_e32 v72, v64, v64
	v_max_f32_e32 v64, 0, v69
	v_mul_f32_e32 v69, v65, v65
	v_max_f32_e32 v65, 0, v70
	v_mul_f32_e32 v70, v66, v66
	v_max_f32_e32 v66, 0, v71
	v_mul_f32_e32 v64, v64, v64
	v_mul_f32_e32 v65, v65, v65
	v_mul_f32_e32 v66, v66, v66
	v_max_f32_e32 v67, 0, v67
	v_cvt_pk_bf16_f32 v64, v68, v64
	v_cvt_pk_bf16_f32 v65, v65, v66
	v_cvt_pk_bf16_f32 v66, v72, v69
	v_lshl_add_u64 v[68:69], v[116:117], 0, v[176:177]
	v_mul_f32_e32 v67, v67, v67
	v_lshl_add_u64 v[68:69], v[68:69], 0, v[140:141]
	v_cvt_pk_bf16_f32 v67, v70, v67
	global_store_dwordx4 v[68:69], v[64:67], off
	s_nop 0
	s_nop 0
	v_add_u32_e32 v66, 0x80, v142
	v_ashrrev_i32_e32 v67, 31, v66
	s_nop 1
	v_fmamk_f32 v64, v223, 0x3a800000, v210
	v_cmp_gt_f32_e32 vcc, s91, v64
	v_mul_f32_e32 v65, 0x4b800000, v64
	s_nop 0
	v_cndmask_b32_e32 v64, v64, v65, vcc
	v_rsq_f32_e32 v64, v64
	s_nop 0
	v_mul_f32_e32 v65, 0x45800000, v64
	v_cndmask_b32_e32 v68, v64, v65, vcc
	v_pk_mul_f32 v[58:59], v[58:59], v[68:69] op_sel_hi:[1,0]
	v_pk_mul_f32 v[56:57], v[56:57], v[68:69] op_sel_hi:[1,0]
	v_pk_mul_f32 v[62:63], v[62:63], v[68:69] op_sel_hi:[1,0]
	v_pk_mul_f32 v[60:61], v[60:61], v[68:69] op_sel_hi:[1,0]
	v_max_f32_e32 v56, 0, v56
	v_max_f32_e32 v57, 0, v57
	v_max_f32_e32 v58, 0, v58
	v_lshrrev_b64 v[64:65], 2, v[66:67]
	v_max_f32_e32 v60, 0, v60
	v_mul_f32_e32 v67, v56, v56
	v_max_f32_e32 v56, 0, v61
; __device__ __forceinline__ unsigned cvt_pk_bf16(float lo, float hi) { unsigned r; asm volatile("v_cvt_pk_bf16_f32 %0, %1, %2" : "=v"(r) : "v"(lo), "v"(hi)); return r; }
;     __device__ __forceinline__ void operator()(const f32x4 (&acc)[2][2][4][2], const Unit& u, int wr, int wc, int fr, int fq) const {
;         const int row0 = u.pm * BM + wr * 64 + fr, col0 = u.pn * BM + wc * 32 + 8 * fq;
; #pragma unroll
;         for (int ai = 0; ai < 2; ++ai)
; #pragma unroll
;             for (int m = 0; m < 4; ++m) { const size_t r = (size_t)(row0 + ai * HALF + m * 16);
;                 const float rstd = rsqrtf(ssq[r] * (1.0f / DM) + RMS_EPS);
; #pragma unroll
;                 for (int bj = 0; bj < 2; ++bj) { f32x4 v0 = acc[ai][bj][m][0] * rstd, v1 = acc[ai][bj][m][1] * rstd;
; #pragma unroll
;                     for (int e = 0; e < 4; ++e) { const float a = fmaxf(v0[e], 0.f), b = fmaxf(v1[e], 0.f); v0[e] = a * a; v1[e] = b * b; }
;                     u32x4 w; w.x = cvt_pk_bf16(v0[0], v0[1]); w.y = cvt_pk_bf16(v0[2], v0[3]); w.z = cvt_pk_bf16(v1[0], v1[1]); w.w = cvt_pk_bf16(v1[2], v1[3]);
;                     const int col = col0 + bj * HALF;
;                     *(u32x4*)(O + ((((r >> 8) * (DFF / 64) + (col >> 6)) * 256 + (r & 255)) * 64 + (col & 63))) = w; } }
	v_mul_f32_e32 v61, v57, v57
	v_max_f32_e32 v57, 0, v62
	v_mul_f32_e32 v62, v58, v58
	v_max_f32_e32 v58, 0, v63
	v_and_b32_e32 v65, 0x1ffff, v65
	v_and_b32_e32 v64, 0xffffffc0, v64
	v_mul_f32_e32 v60, v60, v60
	v_mul_f32_e32 v56, v56, v56
	v_mul_f32_e32 v57, v57, v57
	v_max_f32_e32 v59, 0, v59
	v_mul_f32_e32 v58, v58, v58
	v_mul_f32_e32 v59, v59, v59
	v_cvt_pk_bf16_f32 v56, v60, v56
	v_cvt_pk_bf16_f32 v57, v57, v58
	v_cvt_pk_bf16_f32 v58, v67, v61
	v_lshl_add_u64 v[60:61], v[64:65], 0, s[64:65]
	v_cvt_pk_bf16_f32 v59, v62, v59
	v_lshlrev_b64 v[60:61], 15, v[60:61]
	v_lshlrev_b32_e32 v62, 7, v66
	v_lshl_add_u64 v[60:61], s[70:71], 0, v[60:61]
	v_and_b32_e32 v176, 0x7f80, v62
	v_lshl_add_u64 v[60:61], v[60:61], 0, v[176:177]
	v_pk_mul_f32 v[50:51], v[50:51], v[68:69] op_sel_hi:[1,0]
	v_pk_mul_f32 v[48:49], v[48:49], v[68:69] op_sel_hi:[1,0]
	v_lshl_add_u64 v[60:61], v[60:61], 0, v[140:141]
	v_pk_mul_f32 v[54:55], v[54:55], v[68:69] op_sel_hi:[1,0]
	v_pk_mul_f32 v[52:53], v[52:53], v[68:69] op_sel_hi:[1,0]
	v_max_f32_e32 v48, 0, v48
	v_max_f32_e32 v49, 0, v49
	v_max_f32_e32 v50, 0, v50
	global_store_dwordx4 v[60:61], v[56:59], off
	v_max_f32_e32 v52, 0, v52
	v_mul_f32_e32 v52, v52, v52
	v_mul_f32_e32 v56, v48, v48
	v_max_f32_e32 v48, 0, v53
	v_mul_f32_e32 v53, v49, v49
	v_max_f32_e32 v49, 0, v54
	v_mul_f32_e32 v54, v50, v50
	v_max_f32_e32 v50, 0, v55
	v_mul_f32_e32 v48, v48, v48
	v_mul_f32_e32 v49, v49, v49
	v_mul_f32_e32 v50, v50, v50
	v_cvt_pk_bf16_f32 v48, v52, v48
	v_cvt_pk_bf16_f32 v49, v49, v50
	v_cvt_pk_bf16_f32 v50, v56, v53
	v_lshl_add_u64 v[52:53], v[64:65], 0, s[66:67]
	v_lshlrev_b64 v[52:53], 15, v[52:53]
	v_lshl_add_u64 v[52:53], s[70:71], 0, v[52:53]
	v_max_f32_e32 v51, 0, v51
	v_lshl_add_u64 v[52:53], v[52:53], 0, v[176:177]
	v_mul_f32_e32 v51, v51, v51
	v_lshl_add_u64 v[52:53], v[52:53], 0, v[140:141]
	v_cvt_pk_bf16_f32 v51, v54, v51
	global_store_dwordx4 v[52:53], v[48:51], off
	s_nop 0
	s_nop 0
	v_add_u32_e32 v50, 0x90, v142
	v_ashrrev_i32_e32 v51, 31, v50
	s_nop 1
	v_fmamk_f32 v48, v224, 0x3a800000, v210
	v_cmp_gt_f32_e32 vcc, s91, v48
	v_mul_f32_e32 v49, 0x4b800000, v48
	s_nop 0
	v_cndmask_b32_e32 v48, v48, v49, vcc
	v_rsq_f32_e32 v48, v48
	s_nop 0
	v_mul_f32_e32 v49, 0x45800000, v48
	v_cndmask_b32_e32 v52, v48, v49, vcc
	v_pk_mul_f32 v[42:43], v[42:43], v[52:53] op_sel_hi:[1,0]
	v_pk_mul_f32 v[40:41], v[40:41], v[52:53] op_sel_hi:[1,0]
	v_pk_mul_f32 v[46:47], v[46:47], v[52:53] op_sel_hi:[1,0]
	v_pk_mul_f32 v[44:45], v[44:45], v[52:53] op_sel_hi:[1,0]
	v_max_f32_e32 v40, 0, v40
	v_max_f32_e32 v41, 0, v41
	v_max_f32_e32 v42, 0, v42
	v_lshrrev_b64 v[48:49], 2, v[50:51]
	v_max_f32_e32 v44, 0, v44
	v_mul_f32_e32 v51, v40, v40
	v_max_f32_e32 v40, 0, v45
	v_mul_f32_e32 v45, v41, v41
	v_max_f32_e32 v41, 0, v46
	v_mul_f32_e32 v46, v42, v42
	v_max_f32_e32 v42, 0, v47
	v_and_b32_e32 v49, 0x1ffff, v49
	v_and_b32_e32 v48, 0xffffffc0, v48
	v_mul_f32_e32 v44, v44, v44
	v_mul_f32_e32 v40, v40, v40
	v_mul_f32_e32 v41, v41, v41
	v_max_f32_e32 v43, 0, v43
	v_mul_f32_e32 v42, v42, v42
	v_mul_f32_e32 v43, v43, v43
	v_cvt_pk_bf16_f32 v40, v44, v40
	v_cvt_pk_bf16_f32 v41, v41, v42
	v_cvt_pk_bf16_f32 v42, v51, v45
	v_lshl_add_u64 v[44:45], v[48:49], 0, s[64:65]
	v_cvt_pk_bf16_f32 v43, v46, v43
	v_lshlrev_b64 v[44:45], 15, v[44:45]
	v_lshlrev_b32_e32 v46, 7, v50
	v_lshl_add_u64 v[44:45], s[70:71], 0, v[44:45]
	v_and_b32_e32 v176, 0x7f80, v46
	v_lshl_add_u64 v[44:45], v[44:45], 0, v[176:177]
	v_pk_mul_f32 v[34:35], v[34:35], v[52:53] op_sel_hi:[1,0]
	v_pk_mul_f32 v[32:33], v[32:33], v[52:53] op_sel_hi:[1,0]
	v_lshl_add_u64 v[44:45], v[44:45], 0, v[140:141]
	v_pk_mul_f32 v[38:39], v[38:39], v[52:53] op_sel_hi:[1,0]
	v_pk_mul_f32 v[36:37], v[36:37], v[52:53] op_sel_hi:[1,0]
	v_max_f32_e32 v32, 0, v32
	v_max_f32_e32 v33, 0, v33
	v_max_f32_e32 v34, 0, v34
	global_store_dwordx4 v[44:45], v[40:43], off
	v_max_f32_e32 v36, 0, v36
	v_mul_f32_e32 v36, v36, v36
	v_mul_f32_e32 v40, v32, v32
	v_max_f32_e32 v32, 0, v37
	v_mul_f32_e32 v37, v33, v33
	v_max_f32_e32 v33, 0, v38
	v_mul_f32_e32 v38, v34, v34
	v_max_f32_e32 v34, 0, v39
	v_mul_f32_e32 v32, v32, v32
	v_mul_f32_e32 v33, v33, v33
	v_mul_f32_e32 v34, v34, v34
	v_cvt_pk_bf16_f32 v32, v36, v32
	v_cvt_pk_bf16_f32 v33, v33, v34
	v_cvt_pk_bf16_f32 v34, v40, v37
	v_lshl_add_u64 v[36:37], v[48:49], 0, s[66:67]
	v_lshlrev_b64 v[36:37], 15, v[36:37]
	v_lshl_add_u64 v[36:37], s[70:71], 0, v[36:37]
	v_max_f32_e32 v35, 0, v35
	v_lshl_add_u64 v[36:37], v[36:37], 0, v[176:177]
	v_mul_f32_e32 v35, v35, v35
	v_lshl_add_u64 v[36:37], v[36:37], 0, v[140:141]
	v_cvt_pk_bf16_f32 v35, v38, v35
	global_store_dwordx4 v[36:37], v[32:35], off
	s_nop 0
	s_nop 0
	v_add_u32_e32 v34, 0xa0, v142
	v_ashrrev_i32_e32 v35, 31, v34
	s_nop 1
	v_fmamk_f32 v32, v225, 0x3a800000, v210
	v_cmp_gt_f32_e32 vcc, s91, v32
	v_mul_f32_e32 v33, 0x4b800000, v32
	s_nop 0
	v_cndmask_b32_e32 v32, v32, v33, vcc
	v_rsq_f32_e32 v32, v32
	s_nop 0
	v_mul_f32_e32 v33, 0x45800000, v32
	v_cndmask_b32_e32 v36, v32, v33, vcc
	v_pk_mul_f32 v[26:27], v[26:27], v[36:37] op_sel_hi:[1,0]
; __device__ __forceinline__ unsigned cvt_pk_bf16(float lo, float hi) { unsigned r; asm volatile("v_cvt_pk_bf16_f32 %0, %1, %2" : "=v"(r) : "v"(lo), "v"(hi)); return r; }
;     __device__ __forceinline__ void operator()(const f32x4 (&acc)[2][2][4][2], const Unit& u, int wr, int wc, int fr, int fq) const {
;         const int row0 = u.pm * BM + wr * 64 + fr, col0 = u.pn * BM + wc * 32 + 8 * fq;
; #pragma unroll
;         for (int ai = 0; ai < 2; ++ai)
; #pragma unroll
;             for (int m = 0; m < 4; ++m) { const size_t r = (size_t)(row0 + ai * HALF + m * 16);
;                 const float rstd = rsqrtf(ssq[r] * (1.0f / DM) + RMS_EPS);
; #pragma unroll
;                 for (int bj = 0; bj < 2; ++bj) { f32x4 v0 = acc[ai][bj][m][0] * rstd, v1 = acc[ai][bj][m][1] * rstd;
; #pragma unroll
;                     for (int e = 0; e < 4; ++e) { const float a = fmaxf(v0[e], 0.f), b = fmaxf(v1[e], 0.f); v0[e] = a * a; v1[e] = b * b; }
;                     u32x4 w; w.x = cvt_pk_bf16(v0[0], v0[1]); w.y = cvt_pk_bf16(v0[2], v0[3]); w.z = cvt_pk_bf16(v1[0], v1[1]); w.w = cvt_pk_bf16(v1[2], v1[3]);
;                     const int col = col0 + bj * HALF;
;                     *(u32x4*)(O + ((((r >> 8) * (DFF / 64) + (col >> 6)) * 256 + (r & 255)) * 64 + (col & 63))) = w; } }
	v_pk_mul_f32 v[24:25], v[24:25], v[36:37] op_sel_hi:[1,0]
	v_pk_mul_f32 v[30:31], v[30:31], v[36:37] op_sel_hi:[1,0]
	v_pk_mul_f32 v[28:29], v[28:29], v[36:37] op_sel_hi:[1,0]
	v_max_f32_e32 v24, 0, v24
	v_max_f32_e32 v25, 0, v25
	v_max_f32_e32 v26, 0, v26
	v_lshrrev_b64 v[32:33], 2, v[34:35]
	v_max_f32_e32 v28, 0, v28
	v_mul_f32_e32 v35, v24, v24
	v_max_f32_e32 v24, 0, v29
	v_mul_f32_e32 v29, v25, v25
	v_max_f32_e32 v25, 0, v30
	v_mul_f32_e32 v30, v26, v26
	v_max_f32_e32 v26, 0, v31
	v_and_b32_e32 v33, 0x1ffff, v33
	v_and_b32_e32 v32, 0xffffffc0, v32
	v_mul_f32_e32 v28, v28, v28
	v_mul_f32_e32 v24, v24, v24
	v_mul_f32_e32 v25, v25, v25
	v_max_f32_e32 v27, 0, v27
	v_mul_f32_e32 v26, v26, v26
	v_mul_f32_e32 v27, v27, v27
	v_cvt_pk_bf16_f32 v24, v28, v24
	v_cvt_pk_bf16_f32 v25, v25, v26
	v_cvt_pk_bf16_f32 v26, v35, v29
	v_lshl_add_u64 v[28:29], v[32:33], 0, s[64:65]
	v_cvt_pk_bf16_f32 v27, v30, v27
	v_lshlrev_b64 v[28:29], 15, v[28:29]
	v_lshlrev_b32_e32 v30, 7, v34
	v_lshl_add_u64 v[28:29], s[70:71], 0, v[28:29]
	v_and_b32_e32 v176, 0x7f80, v30
	v_lshl_add_u64 v[28:29], v[28:29], 0, v[176:177]
	v_pk_mul_f32 v[18:19], v[18:19], v[36:37] op_sel_hi:[1,0]
	v_pk_mul_f32 v[16:17], v[16:17], v[36:37] op_sel_hi:[1,0]
	v_lshl_add_u64 v[28:29], v[28:29], 0, v[140:141]
	v_pk_mul_f32 v[22:23], v[22:23], v[36:37] op_sel_hi:[1,0]
	v_pk_mul_f32 v[20:21], v[20:21], v[36:37] op_sel_hi:[1,0]
	v_max_f32_e32 v16, 0, v16
	v_max_f32_e32 v17, 0, v17
	v_max_f32_e32 v18, 0, v18
	global_store_dwordx4 v[28:29], v[24:27], off
	v_max_f32_e32 v20, 0, v20
	v_mul_f32_e32 v20, v20, v20
	v_mul_f32_e32 v24, v16, v16
	v_max_f32_e32 v16, 0, v21
	v_mul_f32_e32 v21, v17, v17
	v_max_f32_e32 v17, 0, v22
	v_mul_f32_e32 v22, v18, v18
	v_max_f32_e32 v18, 0, v23
	v_mul_f32_e32 v16, v16, v16
	v_mul_f32_e32 v17, v17, v17
	v_mul_f32_e32 v18, v18, v18
	v_cvt_pk_bf16_f32 v16, v20, v16
	v_cvt_pk_bf16_f32 v17, v17, v18
	v_cvt_pk_bf16_f32 v18, v24, v21
	v_lshl_add_u64 v[20:21], v[32:33], 0, s[66:67]
	v_lshlrev_b64 v[20:21], 15, v[20:21]
	v_lshl_add_u64 v[20:21], s[70:71], 0, v[20:21]
	v_max_f32_e32 v19, 0, v19
	v_lshl_add_u64 v[20:21], v[20:21], 0, v[176:177]
	v_mul_f32_e32 v19, v19, v19
	v_lshl_add_u64 v[20:21], v[20:21], 0, v[140:141]
	v_cvt_pk_bf16_f32 v19, v22, v19
	global_store_dwordx4 v[20:21], v[16:19], off
	s_nop 0
	s_nop 0
	v_add_u32_e32 v16, 0xb0, v142
	v_ashrrev_i32_e32 v17, 31, v16
	v_lshrrev_b64 v[20:21], 2, v[16:17]
	v_and_b32_e32 v21, 0x1ffff, v21
	v_and_b32_e32 v20, 0xffffffc0, v20
	s_nop 1
	v_fmamk_f32 v18, v226, 0x3a800000, v210
	v_cmp_gt_f32_e32 vcc, s91, v18
	v_mul_f32_e32 v19, 0x4b800000, v18
	s_nop 0
	v_cndmask_b32_e32 v18, v18, v19, vcc
	v_rsq_f32_e32 v18, v18
	s_nop 0
	v_mul_f32_e32 v19, 0x45800000, v18
	v_cndmask_b32_e32 v18, v18, v19, vcc
	v_pk_mul_f32 v[10:11], v[10:11], v[18:19] op_sel_hi:[1,0]
	v_pk_mul_f32 v[8:9], v[8:9], v[18:19] op_sel_hi:[1,0]
	v_pk_mul_f32 v[14:15], v[14:15], v[18:19] op_sel_hi:[1,0]
	v_pk_mul_f32 v[12:13], v[12:13], v[18:19] op_sel_hi:[1,0]
	v_max_f32_e32 v8, 0, v8
	v_max_f32_e32 v9, 0, v9
	v_max_f32_e32 v10, 0, v10
	v_max_f32_e32 v12, 0, v12
	v_mul_f32_e32 v17, v8, v8
	v_max_f32_e32 v8, 0, v13
	v_mul_f32_e32 v13, v9, v9
	v_max_f32_e32 v9, 0, v14
	v_mul_f32_e32 v14, v10, v10
	v_max_f32_e32 v10, 0, v15
	v_mul_f32_e32 v12, v12, v12
	v_mul_f32_e32 v8, v8, v8
	v_mul_f32_e32 v9, v9, v9
	v_max_f32_e32 v11, 0, v11
	v_mul_f32_e32 v10, v10, v10
	v_mul_f32_e32 v11, v11, v11
	v_cvt_pk_bf16_f32 v8, v12, v8
	v_cvt_pk_bf16_f32 v9, v9, v10
	v_cvt_pk_bf16_f32 v10, v17, v13
	v_lshl_add_u64 v[12:13], v[20:21], 0, s[64:65]
	v_cvt_pk_bf16_f32 v11, v14, v11
	v_lshlrev_b64 v[12:13], 15, v[12:13]
	v_lshlrev_b32_e32 v14, 7, v16
	v_lshl_add_u64 v[12:13], s[70:71], 0, v[12:13]
	v_and_b32_e32 v176, 0x7f80, v14
	v_lshl_add_u64 v[12:13], v[12:13], 0, v[176:177]
	v_pk_mul_f32 v[2:3], v[2:3], v[18:19] op_sel_hi:[1,0]
	v_pk_mul_f32 v[0:1], v[0:1], v[18:19] op_sel_hi:[1,0]
	v_lshl_add_u64 v[12:13], v[12:13], 0, v[140:141]
	v_pk_mul_f32 v[6:7], v[6:7], v[18:19] op_sel_hi:[1,0]
	v_pk_mul_f32 v[4:5], v[4:5], v[18:19] op_sel_hi:[1,0]
	v_max_f32_e32 v0, 0, v0
	v_max_f32_e32 v1, 0, v1
	v_max_f32_e32 v2, 0, v2
	global_store_dwordx4 v[12:13], v[8:11], off
	v_max_f32_e32 v4, 0, v4
	v_mul_f32_e32 v4, v4, v4
	v_mul_f32_e32 v8, v0, v0
	v_max_f32_e32 v0, 0, v5
	v_mul_f32_e32 v5, v1, v1
	v_max_f32_e32 v1, 0, v6
	v_mul_f32_e32 v6, v2, v2
	v_max_f32_e32 v2, 0, v7
	v_mul_f32_e32 v0, v0, v0
	v_mul_f32_e32 v1, v1, v1
	v_mul_f32_e32 v2, v2, v2
	v_cvt_pk_bf16_f32 v0, v4, v0
	v_cvt_pk_bf16_f32 v1, v1, v2
	v_cvt_pk_bf16_f32 v2, v8, v5
	v_lshl_add_u64 v[4:5], v[20:21], 0, s[66:67]
	v_lshlrev_b64 v[4:5], 15, v[4:5]
	v_lshl_add_u64 v[4:5], s[70:71], 0, v[4:5]
	v_max_f32_e32 v3, 0, v3
	v_lshl_add_u64 v[4:5], v[4:5], 0, v[176:177]
	v_mul_f32_e32 v3, v3, v3
	v_lshl_add_u64 v[4:5], v[4:5], 0, v[140:141]
	s_andn2_b64 vcc, exec, s[42:43]
	v_cvt_pk_bf16_f32 v3, v6, v3
	global_store_dwordx4 v[4:5], v[0:3], off
	s_cbranch_vccnz .LBB0_800
	s_andn2_b64 vcc, exec, s[14:15]
	s_cbranch_vccnz .LBB0_799
	s_barrier
	s_branch .LBB0_799

;     __device__ __forceinline__ void operator()(const f32x4 (&acc_)[2][2][4][2], const Unit& u, int wr, int wc, int fr, int fq) const {
;     ...
; #pragma unroll
;         for (int ai = 0; ai < 2; ++ai)
; #pragma unroll
;             for (int m = 0; m < 4; ++m) { const size_t r = (size_t)(u.pm * BM + ai * HALF + wr * 64 + m * 16 + fr);
;                 const float rstd = rsqrtf(__hip_atomic_load(ssq + r, __ATOMIC_RELAXED, __HIP_MEMORY_SCOPE_AGENT) * (1.0f / DM) + RMS_EPS);
; #pragma unroll
;                 for (int bj = 0; bj < 2; ++bj)
; #pragma unroll
;                     for (int n = 0; n < 2; ++n) { const size_t off = r * DM + col0 + bj * HALF + n * 16; const f32x4 gg = *(const f32x4*)(gain + col0 + bj * HALF + n * 16);
;                         *(f32x4*)(out + off) = acc[ai][bj][m][n] * rstd * gg; }
;                 asm volatile("" ::: "memory"); }
.LBB0_909:
	s_nop 0
	v_readlane_b32 s64, v249, 40
	s_waitcnt lgkmcnt(0)
	v_lshlrev_b64 v[154:155], 2, v[142:143]
	v_readlane_b32 s65, v249, 41
	v_lshlrev_b64 v[140:141], 12, v[140:141]
	v_lshl_add_u64 v[140:141], s[36:37], 0, v[140:141]
	v_lshl_add_u64 v[142:143], s[64:65], 0, v[154:155]
	s_nop 0
	global_load_dword v226, v[112:113], off sc1
	global_load_dword v227, v[112:113], off offset:64 sc1
	global_load_dword v228, v[112:113], off offset:128 sc1
	global_load_dword v229, v[112:113], off offset:192 sc1
	global_load_dword v230, v[112:113], off offset:512 sc1
	global_load_dword v231, v[112:113], off offset:576 sc1
	global_load_dword v252, v[112:113], off offset:640 sc1
	global_load_dword v253, v[112:113], off offset:704 sc1
	global_load_dwordx4 v[232:235], v[142:143], off
	global_load_dwordx4 v[236:239], v[142:143], off offset:64
	global_load_dwordx4 v[240:243], v[142:143], off offset:512
	global_load_dwordx4 v[244:247], v[142:143], off offset:576
	s_waitcnt vmcnt(0)
	v_lshl_add_u64 v[140:141], v[140:141], 0, v[154:155]
	s_mov_b64 s[0:1], -1
	v_readlane_b32 s66, v249, 42
	v_readlane_b32 s67, v249, 43
	s_nop 0
	v_fmamk_f32 v160, v226, 0x3a800000, v210
	v_mul_f32_e32 v161, 0x4b800000, v160
	v_cmp_gt_f32_e32 vcc, s91, v160
	s_nop 1
	v_cndmask_b32_e32 v160, v160, v161, vcc
	v_rsq_f32_e32 v160, v160
	s_nop 0
	v_mul_f32_e32 v161, 0x45800000, v160
	v_cndmask_b32_e32 v160, v160, v161, vcc
	v_pk_mul_f32 v[124:125], v[124:125], v[160:161] op_sel_hi:[1,0]
	v_pk_mul_f32 v[126:127], v[126:127], v[160:161] op_sel_hi:[1,0]
	s_nop 0
	v_pk_mul_f32 v[124:125], v[232:233], v[124:125]
	v_pk_mul_f32 v[126:127], v[234:235], v[126:127]
	global_store_dwordx4 v[140:141], v[124:127], off
	s_nop 0
	v_pk_mul_f32 v[122:123], v[122:123], v[160:161] op_sel_hi:[1,0]
	v_pk_mul_f32 v[120:121], v[120:121], v[160:161] op_sel_hi:[1,0]
	v_pk_mul_f32 v[118:119], v[118:119], v[160:161] op_sel_hi:[1,0]
	v_pk_mul_f32 v[116:117], v[116:117], v[160:161] op_sel_hi:[1,0]
	s_nop 0
	v_pk_mul_f32 v[120:121], v[236:237], v[120:121]
	v_pk_mul_f32 v[122:123], v[238:239], v[122:123]
	global_store_dwordx4 v[140:141], v[120:123], off offset:64
	s_nop 0
	s_nop 0
	v_pk_mul_f32 v[116:117], v[240:241], v[116:117]
	v_pk_mul_f32 v[118:119], v[242:243], v[118:119]
	global_store_dwordx4 v[140:141], v[116:119], off offset:512
	s_nop 0
	v_pk_mul_f32 v[120:121], v[114:115], v[160:161] op_sel_hi:[1,0]
	v_pk_mul_f32 v[114:115], v[144:145], v[160:161] op_sel_hi:[1,0]
	s_nop 0
	v_pk_mul_f32 v[114:115], v[244:245], v[114:115]
	v_pk_mul_f32 v[116:117], v[246:247], v[120:121]
	global_store_dwordx4 v[140:141], v[114:117], off offset:576
	s_nop 0
	s_nop 0
	s_nop 0
	v_fmamk_f32 v118, v227, 0x3a800000, v210
	v_mul_f32_e32 v119, 0x4b800000, v118
	v_cmp_gt_f32_e32 vcc, s91, v118
	s_nop 1
	v_cndmask_b32_e32 v118, v118, v119, vcc
	v_rsq_f32_e32 v120, v118
	v_lshlrev_b64 v[118:119], 12, v[138:139]
	v_lshl_add_u64 v[118:119], s[36:37], 0, v[118:119]
	v_lshl_add_u64 v[118:119], v[118:119], 0, v[154:155]
	v_mul_f32_e32 v121, 0x45800000, v120
	v_cndmask_b32_e32 v120, v120, v121, vcc
	v_pk_mul_f32 v[108:109], v[108:109], v[120:121] op_sel_hi:[1,0]
	v_pk_mul_f32 v[110:111], v[110:111], v[120:121] op_sel_hi:[1,0]
	s_nop 0
	v_pk_mul_f32 v[108:109], v[232:233], v[108:109]
	v_pk_mul_f32 v[110:111], v[234:235], v[110:111]
	global_store_dwordx4 v[118:119], v[108:111], off
	s_nop 0
	v_pk_mul_f32 v[106:107], v[106:107], v[120:121] op_sel_hi:[1,0]
	v_pk_mul_f32 v[104:105], v[104:105], v[120:121] op_sel_hi:[1,0]
	v_pk_mul_f32 v[102:103], v[102:103], v[120:121] op_sel_hi:[1,0]
	v_pk_mul_f32 v[100:101], v[100:101], v[120:121] op_sel_hi:[1,0]
	v_pk_mul_f32 v[98:99], v[98:99], v[120:121] op_sel_hi:[1,0]
	v_pk_mul_f32 v[96:97], v[96:97], v[120:121] op_sel_hi:[1,0]
	s_nop 0
	v_pk_mul_f32 v[104:105], v[236:237], v[104:105]
	v_pk_mul_f32 v[106:107], v[238:239], v[106:107]
	global_store_dwordx4 v[118:119], v[104:107], off offset:64
	s_nop 0
	s_nop 0
	v_pk_mul_f32 v[100:101], v[240:241], v[100:101]
	v_pk_mul_f32 v[102:103], v[242:243], v[102:103]
	global_store_dwordx4 v[118:119], v[100:103], off offset:512
	s_nop 0
	s_nop 0
	v_pk_mul_f32 v[96:97], v[244:245], v[96:97]
	v_pk_mul_f32 v[98:99], v[246:247], v[98:99]
	global_store_dwordx4 v[118:119], v[96:99], off offset:576
	s_nop 0
	s_nop 0
	s_nop 0
	v_fmamk_f32 v100, v228, 0x3a800000, v210
	v_mul_f32_e32 v101, 0x4b800000, v100
	v_cmp_gt_f32_e32 vcc, s91, v100
	s_nop 1
	v_cndmask_b32_e32 v100, v100, v101, vcc
	v_rsq_f32_e32 v102, v100
	v_lshlrev_b64 v[100:101], 12, v[136:137]
	v_lshl_add_u64 v[100:101], s[36:37], 0, v[100:101]
	v_lshl_add_u64 v[100:101], v[100:101], 0, v[154:155]
	v_mul_f32_e32 v103, 0x45800000, v102
	v_cndmask_b32_e32 v102, v102, v103, vcc
	v_pk_mul_f32 v[92:93], v[92:93], v[102:103] op_sel_hi:[1,0]
	v_pk_mul_f32 v[94:95], v[94:95], v[102:103] op_sel_hi:[1,0]
	s_nop 0
	v_pk_mul_f32 v[92:93], v[232:233], v[92:93]
	v_pk_mul_f32 v[94:95], v[234:235], v[94:95]
	global_store_dwordx4 v[100:101], v[92:95], off
	s_nop 0
	v_pk_mul_f32 v[90:91], v[90:91], v[102:103] op_sel_hi:[1,0]
	v_pk_mul_f32 v[88:89], v[88:89], v[102:103] op_sel_hi:[1,0]
	v_pk_mul_f32 v[86:87], v[86:87], v[102:103] op_sel_hi:[1,0]
	v_pk_mul_f32 v[84:85], v[84:85], v[102:103] op_sel_hi:[1,0]
	v_pk_mul_f32 v[82:83], v[82:83], v[102:103] op_sel_hi:[1,0]
	v_pk_mul_f32 v[80:81], v[80:81], v[102:103] op_sel_hi:[1,0]
	s_nop 0
	v_pk_mul_f32 v[88:89], v[236:237], v[88:89]
	v_pk_mul_f32 v[90:91], v[238:239], v[90:91]
	global_store_dwordx4 v[100:101], v[88:91], off offset:64
	s_nop 0
	s_nop 0
	v_pk_mul_f32 v[84:85], v[240:241], v[84:85]
	v_pk_mul_f32 v[86:87], v[242:243], v[86:87]
	global_store_dwordx4 v[100:101], v[84:87], off offset:512
;     __device__ __forceinline__ void operator()(const f32x4 (&acc_)[2][2][4][2], const Unit& u, int wr, int wc, int fr, int fq) const {
;     ...
;         for (int ai = 0; ai < 2; ++ai)
; #pragma unroll
;             for (int m = 0; m < 4; ++m) { const size_t r = (size_t)(u.pm * BM + ai * HALF + wr * 64 + m * 16 + fr);
;                 const float rstd = rsqrtf(__hip_atomic_load(ssq + r, __ATOMIC_RELAXED, __HIP_MEMORY_SCOPE_AGENT) * (1.0f / DM) + RMS_EPS);
; #pragma unroll
;                 for (int bj = 0; bj < 2; ++bj)
; #pragma unroll
;                     for (int n = 0; n < 2; ++n) { const size_t off = r * DM + col0 + bj * HALF + n * 16; const f32x4 gg = *(const f32x4*)(gain + col0 + bj * HALF + n * 16);
;                         *(f32x4*)(out + off) = acc[ai][bj][m][n] * rstd * gg; }
	s_nop 0
	s_nop 0
	v_pk_mul_f32 v[80:81], v[244:245], v[80:81]
	v_pk_mul_f32 v[82:83], v[246:247], v[82:83]
	global_store_dwordx4 v[100:101], v[80:83], off offset:576
	s_nop 0
	s_nop 0
	s_nop 0
	v_fmamk_f32 v84, v229, 0x3a800000, v210
	v_mul_f32_e32 v85, 0x4b800000, v84
	v_cmp_gt_f32_e32 vcc, s91, v84
	s_nop 1
	v_cndmask_b32_e32 v84, v84, v85, vcc
	v_rsq_f32_e32 v86, v84
	v_lshlrev_b64 v[84:85], 12, v[134:135]
	v_lshl_add_u64 v[84:85], s[36:37], 0, v[84:85]
	v_lshl_add_u64 v[84:85], v[84:85], 0, v[154:155]
	v_mul_f32_e32 v87, 0x45800000, v86
	v_cndmask_b32_e32 v86, v86, v87, vcc
	v_pk_mul_f32 v[76:77], v[76:77], v[86:87] op_sel_hi:[1,0]
	v_pk_mul_f32 v[78:79], v[78:79], v[86:87] op_sel_hi:[1,0]
	s_nop 0
	v_pk_mul_f32 v[76:77], v[232:233], v[76:77]
	v_pk_mul_f32 v[78:79], v[234:235], v[78:79]
	global_store_dwordx4 v[84:85], v[76:79], off
	s_nop 0
	v_pk_mul_f32 v[80:81], v[146:147], v[86:87] op_sel_hi:[1,0]
	v_pk_mul_f32 v[72:73], v[72:73], v[86:87] op_sel_hi:[1,0]
	v_pk_mul_f32 v[70:71], v[70:71], v[86:87] op_sel_hi:[1,0]
	s_nop 0
	v_pk_mul_f32 v[76:77], v[236:237], v[72:73]
	v_pk_mul_f32 v[78:79], v[238:239], v[80:81]
	global_store_dwordx4 v[84:85], v[76:79], off offset:64
	s_nop 0
	v_pk_mul_f32 v[80:81], v[148:149], v[86:87] op_sel_hi:[1,0]
	v_pk_mul_f32 v[72:73], v[74:75], v[86:87] op_sel_hi:[1,0]
	s_nop 0
	v_pk_mul_f32 v[74:75], v[242:243], v[80:81]
	v_pk_mul_f32 v[72:73], v[240:241], v[72:73]
	global_store_dwordx4 v[84:85], v[72:75], off offset:512
	s_nop 0
	v_pk_mul_f32 v[76:77], v[150:151], v[86:87] op_sel_hi:[1,0]
	s_nop 0
	v_pk_mul_f32 v[70:71], v[244:245], v[70:71]
	v_pk_mul_f32 v[72:73], v[246:247], v[76:77]
	global_store_dwordx4 v[84:85], v[70:73], off offset:576
	s_nop 0
	s_nop 0
	s_nop 0
	v_fmamk_f32 v74, v230, 0x3a800000, v210
	v_mul_f32_e32 v75, 0x4b800000, v74
	v_cmp_gt_f32_e32 vcc, s91, v74
	s_nop 1
	v_cndmask_b32_e32 v74, v74, v75, vcc
	v_rsq_f32_e32 v76, v74
	v_lshlrev_b64 v[74:75], 12, v[152:153]
	v_lshl_add_u64 v[74:75], s[36:37], 0, v[74:75]
	v_lshl_add_u64 v[74:75], v[74:75], 0, v[154:155]
	v_mul_f32_e32 v77, 0x45800000, v76
	v_cndmask_b32_e32 v76, v76, v77, vcc
	v_pk_mul_f32 v[60:61], v[60:61], v[76:77] op_sel_hi:[1,0]
	v_pk_mul_f32 v[62:63], v[62:63], v[76:77] op_sel_hi:[1,0]
	s_nop 0
	v_pk_mul_f32 v[60:61], v[232:233], v[60:61]
	v_pk_mul_f32 v[62:63], v[234:235], v[62:63]
	global_store_dwordx4 v[74:75], v[60:63], off
	s_nop 0
	v_pk_mul_f32 v[58:59], v[58:59], v[76:77] op_sel_hi:[1,0]
	v_pk_mul_f32 v[56:57], v[56:57], v[76:77] op_sel_hi:[1,0]
	v_pk_mul_f32 v[54:55], v[54:55], v[76:77] op_sel_hi:[1,0]
	v_pk_mul_f32 v[52:53], v[52:53], v[76:77] op_sel_hi:[1,0]
	v_pk_mul_f32 v[50:51], v[50:51], v[76:77] op_sel_hi:[1,0]
	v_pk_mul_f32 v[48:49], v[48:49], v[76:77] op_sel_hi:[1,0]
	s_nop 0
	v_pk_mul_f32 v[56:57], v[236:237], v[56:57]
	v_pk_mul_f32 v[58:59], v[238:239], v[58:59]
	global_store_dwordx4 v[74:75], v[56:59], off offset:64
	s_nop 0
	s_nop 0
	v_pk_mul_f32 v[52:53], v[240:241], v[52:53]
	v_pk_mul_f32 v[54:55], v[242:243], v[54:55]
	global_store_dwordx4 v[74:75], v[52:55], off offset:512
	s_nop 0
	s_nop 0
	v_pk_mul_f32 v[48:49], v[244:245], v[48:49]
	v_pk_mul_f32 v[50:51], v[246:247], v[50:51]
	global_store_dwordx4 v[74:75], v[48:51], off offset:576
	s_nop 0
	s_nop 0
	s_nop 0
	v_fmamk_f32 v52, v231, 0x3a800000, v210
	v_mul_f32_e32 v53, 0x4b800000, v52
	v_cmp_gt_f32_e32 vcc, s91, v52
	s_nop 1
	v_cndmask_b32_e32 v52, v52, v53, vcc
	v_rsq_f32_e32 v54, v52
	v_lshlrev_b64 v[52:53], 12, v[68:69]
	v_lshl_add_u64 v[52:53], s[36:37], 0, v[52:53]
	v_lshl_add_u64 v[52:53], v[52:53], 0, v[154:155]
	v_mul_f32_e32 v55, 0x45800000, v54
	v_cndmask_b32_e32 v54, v54, v55, vcc
	v_pk_mul_f32 v[44:45], v[44:45], v[54:55] op_sel_hi:[1,0]
	v_pk_mul_f32 v[46:47], v[46:47], v[54:55] op_sel_hi:[1,0]
	s_nop 0
	v_pk_mul_f32 v[44:45], v[232:233], v[44:45]
	v_pk_mul_f32 v[46:47], v[234:235], v[46:47]
	global_store_dwordx4 v[52:53], v[44:47], off
	s_nop 0
	v_pk_mul_f32 v[42:43], v[42:43], v[54:55] op_sel_hi:[1,0]
;     __device__ __forceinline__ void operator()(const f32x4 (&acc_)[2][2][4][2], const Unit& u, int wr, int wc, int fr, int fq) const {
;     ...
;         for (int ai = 0; ai < 2; ++ai)
; #pragma unroll
;             for (int m = 0; m < 4; ++m) { const size_t r = (size_t)(u.pm * BM + ai * HALF + wr * 64 + m * 16 + fr);
;                 const float rstd = rsqrtf(__hip_atomic_load(ssq + r, __ATOMIC_RELAXED, __HIP_MEMORY_SCOPE_AGENT) * (1.0f / DM) + RMS_EPS);
; #pragma unroll
;                 for (int bj = 0; bj < 2; ++bj)
; #pragma unroll
;                     for (int n = 0; n < 2; ++n) { const size_t off = r * DM + col0 + bj * HALF + n * 16; const f32x4 gg = *(const f32x4*)(gain + col0 + bj * HALF + n * 16);
;                         *(f32x4*)(out + off) = acc[ai][bj][m][n] * rstd * gg; }
	v_pk_mul_f32 v[40:41], v[40:41], v[54:55] op_sel_hi:[1,0]
	v_pk_mul_f32 v[38:39], v[38:39], v[54:55] op_sel_hi:[1,0]
	v_pk_mul_f32 v[36:37], v[36:37], v[54:55] op_sel_hi:[1,0]
	v_pk_mul_f32 v[34:35], v[34:35], v[54:55] op_sel_hi:[1,0]
	v_pk_mul_f32 v[32:33], v[32:33], v[54:55] op_sel_hi:[1,0]
	s_nop 0
	v_pk_mul_f32 v[40:41], v[236:237], v[40:41]
	v_pk_mul_f32 v[42:43], v[238:239], v[42:43]
	global_store_dwordx4 v[52:53], v[40:43], off offset:64
	s_nop 0
	s_nop 0
	v_pk_mul_f32 v[36:37], v[240:241], v[36:37]
	v_pk_mul_f32 v[38:39], v[242:243], v[38:39]
	global_store_dwordx4 v[52:53], v[36:39], off offset:512
	s_nop 0
	s_nop 0
	v_pk_mul_f32 v[32:33], v[244:245], v[32:33]
	v_pk_mul_f32 v[34:35], v[246:247], v[34:35]
	global_store_dwordx4 v[52:53], v[32:35], off offset:576
	s_nop 0
	s_nop 0
	s_nop 0
	v_fmamk_f32 v36, v252, 0x3a800000, v210
	v_mul_f32_e32 v37, 0x4b800000, v36
	v_cmp_gt_f32_e32 vcc, s91, v36
	s_nop 1
	v_cndmask_b32_e32 v36, v36, v37, vcc
	v_rsq_f32_e32 v38, v36
	v_lshlrev_b64 v[36:37], 12, v[66:67]
	v_lshl_add_u64 v[36:37], s[36:37], 0, v[36:37]
	v_lshl_add_u64 v[36:37], v[36:37], 0, v[154:155]
	v_mul_f32_e32 v39, 0x45800000, v38
	v_cndmask_b32_e32 v38, v38, v39, vcc
	v_pk_mul_f32 v[28:29], v[28:29], v[38:39] op_sel_hi:[1,0]
	v_pk_mul_f32 v[30:31], v[30:31], v[38:39] op_sel_hi:[1,0]
	s_nop 0
	v_pk_mul_f32 v[28:29], v[232:233], v[28:29]
	v_pk_mul_f32 v[30:31], v[234:235], v[30:31]
	global_store_dwordx4 v[36:37], v[28:31], off
	s_nop 0
	v_pk_mul_f32 v[26:27], v[26:27], v[38:39] op_sel_hi:[1,0]
	v_pk_mul_f32 v[24:25], v[24:25], v[38:39] op_sel_hi:[1,0]
	v_pk_mul_f32 v[22:23], v[22:23], v[38:39] op_sel_hi:[1,0]
	v_pk_mul_f32 v[20:21], v[20:21], v[38:39] op_sel_hi:[1,0]
	v_pk_mul_f32 v[18:19], v[18:19], v[38:39] op_sel_hi:[1,0]
	v_pk_mul_f32 v[16:17], v[16:17], v[38:39] op_sel_hi:[1,0]
	s_nop 0
	v_pk_mul_f32 v[24:25], v[236:237], v[24:25]
	v_pk_mul_f32 v[26:27], v[238:239], v[26:27]
	global_store_dwordx4 v[36:37], v[24:27], off offset:64
	s_nop 0
	s_nop 0
	v_pk_mul_f32 v[20:21], v[240:241], v[20:21]
	v_pk_mul_f32 v[22:23], v[242:243], v[22:23]
	global_store_dwordx4 v[36:37], v[20:23], off offset:512
	s_nop 0
	s_nop 0
	v_pk_mul_f32 v[16:17], v[244:245], v[16:17]
	v_pk_mul_f32 v[18:19], v[246:247], v[18:19]
	global_store_dwordx4 v[36:37], v[16:19], off offset:576
	s_nop 0
	s_nop 0
	s_nop 0
	v_fmamk_f32 v20, v253, 0x3a800000, v210
	v_mul_f32_e32 v21, 0x4b800000, v20
	v_cmp_gt_f32_e32 vcc, s91, v20
	s_nop 1
	v_cndmask_b32_e32 v20, v20, v21, vcc
	v_rsq_f32_e32 v22, v20
	v_lshlrev_b64 v[20:21], 12, v[64:65]
	v_lshl_add_u64 v[20:21], s[36:37], 0, v[20:21]
	v_lshl_add_u64 v[20:21], v[20:21], 0, v[154:155]
	v_mul_f32_e32 v23, 0x45800000, v22
	v_cndmask_b32_e32 v22, v22, v23, vcc
	v_pk_mul_f32 v[12:13], v[12:13], v[22:23] op_sel_hi:[1,0]
	v_pk_mul_f32 v[14:15], v[14:15], v[22:23] op_sel_hi:[1,0]
	s_nop 0
	v_pk_mul_f32 v[12:13], v[232:233], v[12:13]
	v_pk_mul_f32 v[14:15], v[234:235], v[14:15]
	global_store_dwordx4 v[20:21], v[12:15], off
	s_nop 0
	v_pk_mul_f32 v[10:11], v[10:11], v[22:23] op_sel_hi:[1,0]
	v_pk_mul_f32 v[8:9], v[8:9], v[22:23] op_sel_hi:[1,0]
	v_pk_mul_f32 v[6:7], v[6:7], v[22:23] op_sel_hi:[1,0]
	v_pk_mul_f32 v[4:5], v[4:5], v[22:23] op_sel_hi:[1,0]
	v_pk_mul_f32 v[2:3], v[2:3], v[22:23] op_sel_hi:[1,0]
	v_pk_mul_f32 v[0:1], v[0:1], v[22:23] op_sel_hi:[1,0]
	s_andn2_b64 vcc, exec, s[42:43]
	s_nop 0
	v_pk_mul_f32 v[8:9], v[236:237], v[8:9]
	v_pk_mul_f32 v[10:11], v[238:239], v[10:11]
	global_store_dwordx4 v[20:21], v[8:11], off offset:64
	s_nop 0
	s_nop 0
	v_pk_mul_f32 v[4:5], v[240:241], v[4:5]
	v_pk_mul_f32 v[6:7], v[242:243], v[6:7]
	global_store_dwordx4 v[20:21], v[4:7], off offset:512
	s_nop 0
	s_nop 0
	v_pk_mul_f32 v[0:1], v[244:245], v[0:1]
	v_pk_mul_f32 v[2:3], v[246:247], v[2:3]
	global_store_dwordx4 v[20:21], v[0:3], off offset:576
	s_cbranch_vccnz .LBB0_871
	s_andn2_b64 vcc, exec, s[44:45]
	s_cbranch_vccnz .LBB0_870
	s_barrier
	s_branch .LBB0_870
